# v14 + K-loop load segments reordered: ds_reads first, then m0 writes and LDS-DMA issue
# speedup vs baseline: 1.0041x; 1.0000x over previous
.LBB0_252:
	s_add_u32 s12, s54, 0xfff00080
	s_addc_u32 s13, s55, -1
	s_add_i32 s95, 0, 0x10000
	s_cmp_eq_u32 s94, 60
	s_cselect_b32 s65, s47, s13
	s_cselect_b32 s64, s66, s12
	s_cselect_b32 s63, s45, s61
	s_cselect_b32 s62, vcc_lo, vcc_hi
	s_add_i32 s56, 0, 0x14000
	v_add_u32_e32 v142, s95, v144
	ds_read_b128 v[148:151], v142
	ds_read_b128 v[152:155], v142 offset:1024
	ds_read_b128 v[156:159], v142 offset:2048
	ds_read_b128 v[160:163], v142 offset:3072
	v_add_u32_e32 v142, s56, v144
	ds_read_b128 v[164:167], v142
	ds_read_b128 v[168:171], v142 offset:1024
	ds_read_b128 v[172:175], v142 offset:2048
	ds_read_b128 v[176:179], v142 offset:3072
	ds_read_b128 v[180:183], v146
	ds_read_b128 v[184:187], v146 offset:1024
	ds_read_b128 v[210:213], v146 offset:2048
	ds_read_b128 v[214:217], v146 offset:3072
	ds_read_b128 v[218:221], v146 offset:4096
	ds_read_b128 v[222:225], v146 offset:5120
	ds_read_b128 v[226:229], v146 offset:6144
	ds_read_b128 v[230:233], v146 offset:7168
	s_add_i32 m0, s53, 0xc000
	s_nop 0
	global_load_lds_dwordx4 v136, s[54:55]
	s_add_i32 m0, s53, 0xe000
	s_nop 0
	global_load_lds_dwordx4 v138, s[54:55]
	s_waitcnt vmcnt(8)
	s_waitcnt lgkmcnt(0)
	s_barrier
	s_setprio 1
	s_waitcnt lgkmcnt(0)
	v_mfma_f32_16x16x32_bf16 v[126:129], v[148:151], v[180:183], v[126:129]
	v_mfma_f32_16x16x32_bf16 v[126:129], v[152:155], v[184:187], v[126:129]
	v_mfma_f32_16x16x32_bf16 v[114:117], v[152:155], v[214:217], v[114:117]
	v_mfma_f32_16x16x32_bf16 v[114:117], v[148:151], v[210:213], v[114:117]
	v_mfma_f32_16x16x32_bf16 v[98:101], v[148:151], v[218:221], v[98:101]
	v_mfma_f32_16x16x32_bf16 v[98:101], v[152:155], v[222:225], v[98:101]
	v_mfma_f32_16x16x32_bf16 v[82:85], v[152:155], v[230:233], v[82:85]
	v_mfma_f32_16x16x32_bf16 v[82:85], v[148:151], v[226:229], v[82:85]
	v_mfma_f32_16x16x32_bf16 v[74:77], v[156:159], v[226:229], v[74:77]
	v_mfma_f32_16x16x32_bf16 v[74:77], v[160:163], v[230:233], v[74:77]
	v_mfma_f32_16x16x32_bf16 v[90:93], v[160:163], v[222:225], v[90:93]
	v_mfma_f32_16x16x32_bf16 v[90:93], v[156:159], v[218:221], v[90:93]
	v_mfma_f32_16x16x32_bf16 v[106:109], v[156:159], v[210:213], v[106:109]
	v_mfma_f32_16x16x32_bf16 v[106:109], v[160:163], v[214:217], v[106:109]
	v_mfma_f32_16x16x32_bf16 v[122:125], v[160:163], v[184:187], v[122:125]
	v_mfma_f32_16x16x32_bf16 v[122:125], v[156:159], v[180:183], v[122:125]
	v_mfma_f32_16x16x32_bf16 v[110:113], v[172:175], v[180:183], v[110:113]
	v_mfma_f32_16x16x32_bf16 v[110:113], v[176:179], v[184:187], v[110:113]
	v_mfma_f32_16x16x32_bf16 v[94:97], v[176:179], v[214:217], v[94:97]
	v_mfma_f32_16x16x32_bf16 v[94:97], v[172:175], v[210:213], v[94:97]
	v_mfma_f32_16x16x32_bf16 v[78:81], v[172:175], v[218:221], v[78:81]
	v_mfma_f32_16x16x32_bf16 v[78:81], v[176:179], v[222:225], v[78:81]
	v_mfma_f32_16x16x32_bf16 v[66:69], v[176:179], v[230:233], v[66:69]
	v_mfma_f32_16x16x32_bf16 v[66:69], v[172:175], v[226:229], v[66:69]
	v_mfma_f32_16x16x32_bf16 v[70:73], v[164:167], v[226:229], v[70:73]
	v_mfma_f32_16x16x32_bf16 v[70:73], v[168:171], v[230:233], v[70:73]
	v_mfma_f32_16x16x32_bf16 v[86:89], v[168:171], v[222:225], v[86:89]
	v_mfma_f32_16x16x32_bf16 v[86:89], v[164:167], v[218:221], v[86:89]
	v_mfma_f32_16x16x32_bf16 v[102:105], v[164:167], v[210:213], v[102:105]
	v_mfma_f32_16x16x32_bf16 v[102:105], v[168:171], v[214:217], v[102:105]
	v_mfma_f32_16x16x32_bf16 v[118:121], v[168:171], v[184:187], v[118:121]
	v_mfma_f32_16x16x32_bf16 v[118:121], v[164:167], v[180:183], v[118:121]
	s_setprio 0
	s_barrier
	s_add_i32 s12, s95, s82
	ds_read_b128 v[180:183], v146 offset:16384
	ds_read_b128 v[184:187], v146 offset:17408
	ds_read_b128 v[210:213], v146 offset:18432
	ds_read_b128 v[214:217], v146 offset:19456
	ds_read_b128 v[218:221], v146 offset:20480
	ds_read_b128 v[222:225], v146 offset:21504
	ds_read_b128 v[226:229], v146 offset:22528
	ds_read_b128 v[230:233], v146 offset:23552
	s_mov_b32 m0, s12
	s_nop 0
	global_load_lds_dwordx4 v190, s[62:63]
	s_add_i32 m0, s12, 0x2000
	s_add_u32 s12, s62, 0x100000
	s_addc_u32 s13, s63, 0
	s_add_i32 s56, s56, s82
	global_load_lds_dwordx4 v134, s[62:63]
	s_mov_b32 m0, s56
	s_nop 0
	global_load_lds_dwordx4 v190, s[12:13]
	s_add_i32 m0, s56, 0x2000
	s_nop 0
	global_load_lds_dwordx4 v134, s[12:13]
	s_mov_b32 m0, s53
	s_nop 0
	global_load_lds_dwordx4 v130, s[64:65]
	s_mov_b32 m0, s84
	s_nop 0
	global_load_lds_dwordx4 v132, s[64:65]
	s_waitcnt vmcnt(8)
	s_waitcnt lgkmcnt(0)
	s_barrier
	s_setprio 1
	s_waitcnt lgkmcnt(0)
	v_mfma_f32_16x16x32_bf16 v[62:65], v[148:151], v[180:183], v[62:65]
	v_mfma_f32_16x16x32_bf16 v[62:65], v[152:155], v[184:187], v[62:65]
	v_mfma_f32_16x16x32_bf16 v[50:53], v[152:155], v[214:217], v[50:53]
	v_mfma_f32_16x16x32_bf16 v[50:53], v[148:151], v[210:213], v[50:53]
	v_mfma_f32_16x16x32_bf16 v[34:37], v[148:151], v[218:221], v[34:37]
	v_mfma_f32_16x16x32_bf16 v[34:37], v[152:155], v[222:225], v[34:37]
	v_mfma_f32_16x16x32_bf16 v[18:21], v[152:155], v[230:233], v[18:21]
	v_mfma_f32_16x16x32_bf16 v[18:21], v[148:151], v[226:229], v[18:21]
	v_mfma_f32_16x16x32_bf16 v[10:13], v[156:159], v[226:229], v[10:13]
	v_mfma_f32_16x16x32_bf16 v[10:13], v[160:163], v[230:233], v[10:13]
	v_mfma_f32_16x16x32_bf16 v[26:29], v[160:163], v[222:225], v[26:29]
	v_mfma_f32_16x16x32_bf16 v[26:29], v[156:159], v[218:221], v[26:29]
	v_mfma_f32_16x16x32_bf16 v[42:45], v[156:159], v[210:213], v[42:45]
	v_mfma_f32_16x16x32_bf16 v[42:45], v[160:163], v[214:217], v[42:45]
	v_mfma_f32_16x16x32_bf16 v[58:61], v[160:163], v[184:187], v[58:61]
	v_mfma_f32_16x16x32_bf16 v[58:61], v[156:159], v[180:183], v[58:61]
	v_mfma_f32_16x16x32_bf16 v[46:49], v[172:175], v[180:183], v[46:49]
	v_mfma_f32_16x16x32_bf16 v[46:49], v[176:179], v[184:187], v[46:49]
	v_mfma_f32_16x16x32_bf16 v[30:33], v[176:179], v[214:217], v[30:33]
	v_mfma_f32_16x16x32_bf16 v[30:33], v[172:175], v[210:213], v[30:33]
	v_mfma_f32_16x16x32_bf16 v[14:17], v[172:175], v[218:221], v[14:17]
	v_mfma_f32_16x16x32_bf16 v[14:17], v[176:179], v[222:225], v[14:17]
	v_mfma_f32_16x16x32_bf16 v[2:5], v[176:179], v[230:233], v[2:5]
	v_mfma_f32_16x16x32_bf16 v[2:5], v[172:175], v[226:229], v[2:5]
	v_mfma_f32_16x16x32_bf16 v[6:9], v[164:167], v[226:229], v[6:9]
	v_mfma_f32_16x16x32_bf16 v[6:9], v[168:171], v[230:233], v[6:9]
	v_mfma_f32_16x16x32_bf16 v[22:25], v[168:171], v[222:225], v[22:25]
	v_mfma_f32_16x16x32_bf16 v[22:25], v[164:167], v[218:221], v[22:25]
	v_mfma_f32_16x16x32_bf16 v[38:41], v[164:167], v[210:213], v[38:41]
	v_mfma_f32_16x16x32_bf16 v[38:41], v[168:171], v[214:217], v[38:41]
	v_mfma_f32_16x16x32_bf16 v[54:57], v[168:171], v[184:187], v[54:57]
	v_mfma_f32_16x16x32_bf16 v[54:57], v[164:167], v[180:183], v[54:57]
	s_setprio 0
	s_barrier
	s_add_i32 s56, 0, 0x18000
	s_add_i32 s95, 0, 0x1c000
	s_add_u32 s12, s64, 0x100000
	s_addc_u32 s13, s65, 0
	v_add_u32_e32 v147, s56, v144
	ds_read_b128 v[148:151], v147
	ds_read_b128 v[152:155], v147 offset:1024
	ds_read_b128 v[156:159], v147 offset:2048
	ds_read_b128 v[160:163], v147 offset:3072
	v_add_u32_e32 v147, s95, v144
	ds_read_b128 v[164:167], v147
	ds_read_b128 v[168:171], v147 offset:1024
	ds_read_b128 v[172:175], v147 offset:2048
	ds_read_b128 v[176:179], v147 offset:3072
	ds_read_b128 v[180:183], v146 offset:32768
	ds_read_b128 v[184:187], v146 offset:33792
	ds_read_b128 v[210:213], v146 offset:34816
	ds_read_b128 v[214:217], v146 offset:35840
	ds_read_b128 v[218:221], v146 offset:36864
	ds_read_b128 v[222:225], v146 offset:37888
	ds_read_b128 v[226:229], v146 offset:38912
	ds_read_b128 v[230:233], v146 offset:39936
	s_mov_b32 m0, s85
	s_nop 0
	global_load_lds_dwordx4 v130, s[12:13]
	s_mov_b32 m0, s86
	s_nop 0
	global_load_lds_dwordx4 v132, s[12:13]
	s_waitcnt vmcnt(8)
	s_waitcnt lgkmcnt(0)
	s_barrier
	s_setprio 1
	s_waitcnt lgkmcnt(0)
	v_mfma_f32_16x16x32_bf16 v[126:129], v[148:151], v[180:183], v[126:129]
	v_mfma_f32_16x16x32_bf16 v[126:129], v[152:155], v[184:187], v[126:129]
	v_mfma_f32_16x16x32_bf16 v[114:117], v[152:155], v[214:217], v[114:117]
	v_mfma_f32_16x16x32_bf16 v[114:117], v[148:151], v[210:213], v[114:117]
	v_mfma_f32_16x16x32_bf16 v[98:101], v[148:151], v[218:221], v[98:101]
	v_mfma_f32_16x16x32_bf16 v[98:101], v[152:155], v[222:225], v[98:101]
	v_mfma_f32_16x16x32_bf16 v[82:85], v[152:155], v[230:233], v[82:85]
	v_mfma_f32_16x16x32_bf16 v[82:85], v[148:151], v[226:229], v[82:85]
	v_mfma_f32_16x16x32_bf16 v[74:77], v[156:159], v[226:229], v[74:77]
	v_mfma_f32_16x16x32_bf16 v[74:77], v[160:163], v[230:233], v[74:77]
	v_mfma_f32_16x16x32_bf16 v[90:93], v[160:163], v[222:225], v[90:93]
	v_mfma_f32_16x16x32_bf16 v[90:93], v[156:159], v[218:221], v[90:93]
	v_mfma_f32_16x16x32_bf16 v[106:109], v[156:159], v[210:213], v[106:109]
	v_mfma_f32_16x16x32_bf16 v[106:109], v[160:163], v[214:217], v[106:109]
	v_mfma_f32_16x16x32_bf16 v[122:125], v[160:163], v[184:187], v[122:125]
	v_mfma_f32_16x16x32_bf16 v[122:125], v[156:159], v[180:183], v[122:125]
	v_mfma_f32_16x16x32_bf16 v[110:113], v[172:175], v[180:183], v[110:113]
	v_mfma_f32_16x16x32_bf16 v[110:113], v[176:179], v[184:187], v[110:113]
	v_mfma_f32_16x16x32_bf16 v[94:97], v[176:179], v[214:217], v[94:97]
	v_mfma_f32_16x16x32_bf16 v[94:97], v[172:175], v[210:213], v[94:97]
	v_mfma_f32_16x16x32_bf16 v[78:81], v[172:175], v[218:221], v[78:81]
	v_mfma_f32_16x16x32_bf16 v[78:81], v[176:179], v[222:225], v[78:81]
	v_mfma_f32_16x16x32_bf16 v[66:69], v[176:179], v[230:233], v[66:69]
	v_mfma_f32_16x16x32_bf16 v[66:69], v[172:175], v[226:229], v[66:69]
	v_mfma_f32_16x16x32_bf16 v[70:73], v[164:167], v[226:229], v[70:73]
	v_mfma_f32_16x16x32_bf16 v[70:73], v[168:171], v[230:233], v[70:73]
	v_mfma_f32_16x16x32_bf16 v[86:89], v[168:171], v[222:225], v[86:89]
	v_mfma_f32_16x16x32_bf16 v[86:89], v[164:167], v[218:221], v[86:89]
	v_mfma_f32_16x16x32_bf16 v[102:105], v[164:167], v[210:213], v[102:105]
	v_mfma_f32_16x16x32_bf16 v[102:105], v[168:171], v[214:217], v[102:105]
	v_mfma_f32_16x16x32_bf16 v[118:121], v[168:171], v[184:187], v[118:121]
	v_mfma_f32_16x16x32_bf16 v[118:121], v[164:167], v[180:183], v[118:121]
	s_setprio 0
	s_barrier
	s_add_i32 s12, s56, s82
	ds_read_b128 v[180:183], v146 offset:49152
	ds_read_b128 v[184:187], v146 offset:50176
	ds_read_b128 v[210:213], v146 offset:51200
	ds_read_b128 v[214:217], v146 offset:52224
	ds_read_b128 v[218:221], v146 offset:53248
	ds_read_b128 v[222:225], v146 offset:54272
	ds_read_b128 v[226:229], v146 offset:55296
	ds_read_b128 v[230:233], v146 offset:56320
	s_mov_b32 m0, s12
	s_nop 0
	global_load_lds_dwordx4 v234, s[62:63]
	s_add_i32 m0, s12, 0x2000
	s_add_u32 s12, s62, 0x100080
	s_addc_u32 s13, s63, 0
	s_add_i32 s56, s95, s82
	global_load_lds_dwordx4 v189, s[62:63]
	s_mov_b32 m0, s56
	s_nop 0
	global_load_lds_dwordx4 v190, s[12:13]
	s_add_i32 m0, s56, 0x2000
	s_nop 0
	global_load_lds_dwordx4 v134, s[12:13]
	s_mov_b32 m0, s90
	s_nop 0
	global_load_lds_dwordx4 v143, s[64:65]
	s_mov_b32 m0, s97
	s_nop 0
	global_load_lds_dwordx4 v188, s[64:65]
	s_waitcnt vmcnt(8)
	s_waitcnt lgkmcnt(0)
	s_barrier
	s_setprio 1
	s_waitcnt lgkmcnt(0)
	v_mfma_f32_16x16x32_bf16 v[62:65], v[148:151], v[180:183], v[62:65]
	v_mfma_f32_16x16x32_bf16 v[62:65], v[152:155], v[184:187], v[62:65]
	v_mfma_f32_16x16x32_bf16 v[50:53], v[152:155], v[214:217], v[50:53]
	v_mfma_f32_16x16x32_bf16 v[50:53], v[148:151], v[210:213], v[50:53]
	v_mfma_f32_16x16x32_bf16 v[34:37], v[148:151], v[218:221], v[34:37]
	v_mfma_f32_16x16x32_bf16 v[34:37], v[152:155], v[222:225], v[34:37]
	v_mfma_f32_16x16x32_bf16 v[18:21], v[152:155], v[230:233], v[18:21]
	v_mfma_f32_16x16x32_bf16 v[18:21], v[148:151], v[226:229], v[18:21]
	v_mfma_f32_16x16x32_bf16 v[10:13], v[156:159], v[226:229], v[10:13]
	v_mfma_f32_16x16x32_bf16 v[10:13], v[160:163], v[230:233], v[10:13]
	v_mfma_f32_16x16x32_bf16 v[26:29], v[160:163], v[222:225], v[26:29]
	v_mfma_f32_16x16x32_bf16 v[26:29], v[156:159], v[218:221], v[26:29]
	v_mfma_f32_16x16x32_bf16 v[42:45], v[156:159], v[210:213], v[42:45]
	v_mfma_f32_16x16x32_bf16 v[42:45], v[160:163], v[214:217], v[42:45]
	v_mfma_f32_16x16x32_bf16 v[58:61], v[160:163], v[184:187], v[58:61]
	v_mfma_f32_16x16x32_bf16 v[58:61], v[156:159], v[180:183], v[58:61]
	v_mfma_f32_16x16x32_bf16 v[46:49], v[172:175], v[180:183], v[46:49]
	v_mfma_f32_16x16x32_bf16 v[46:49], v[176:179], v[184:187], v[46:49]
	v_mfma_f32_16x16x32_bf16 v[30:33], v[176:179], v[214:217], v[30:33]
	v_mfma_f32_16x16x32_bf16 v[30:33], v[172:175], v[210:213], v[30:33]
	v_mfma_f32_16x16x32_bf16 v[14:17], v[172:175], v[218:221], v[14:17]
	v_mfma_f32_16x16x32_bf16 v[14:17], v[176:179], v[222:225], v[14:17]
	v_mfma_f32_16x16x32_bf16 v[2:5], v[176:179], v[230:233], v[2:5]
	v_mfma_f32_16x16x32_bf16 v[2:5], v[172:175], v[226:229], v[2:5]
	v_mfma_f32_16x16x32_bf16 v[6:9], v[164:167], v[226:229], v[6:9]
	v_mfma_f32_16x16x32_bf16 v[6:9], v[168:171], v[230:233], v[6:9]
	v_mfma_f32_16x16x32_bf16 v[22:25], v[168:171], v[222:225], v[22:25]
	v_mfma_f32_16x16x32_bf16 v[22:25], v[164:167], v[218:221], v[22:25]
	v_mfma_f32_16x16x32_bf16 v[38:41], v[164:167], v[210:213], v[38:41]
	v_mfma_f32_16x16x32_bf16 v[38:41], v[168:171], v[214:217], v[38:41]
	v_mfma_f32_16x16x32_bf16 v[54:57], v[168:171], v[184:187], v[54:57]
	v_mfma_f32_16x16x32_bf16 v[54:57], v[164:167], v[180:183], v[54:57]
	s_setprio 0
	s_barrier
	s_add_i32 s94, s94, 2
	s_add_u32 s54, s54, 0x100
	s_addc_u32 s55, s55, 0
	s_add_u32 vcc_hi, vcc_hi, 0x100
	s_addc_u32 s61, s61, 0
	s_cmp_gt_u32 s94, 61
	s_cbranch_scc0 .LBB0_252
	s_and_b64 vcc, exec, s[42:43]
	s_cbranch_vccz .LBB0_255
	s_barrier

.LBB0_692:
	s_add_u32 s12, s40, 0xfffc0080
	s_addc_u32 s13, s41, -1
	s_add_i32 s56, 0, 0x10000
	s_cmp_eq_u32 s74, 12
	s_cselect_b32 s63, s47, s13
	s_cselect_b32 s62, s71, s12
	s_cselect_b32 s55, s45, s61
	s_cselect_b32 s54, s72, s73
	s_add_i32 s75, 0, 0x14000
	v_add_u32_e32 v142, s56, v160
	v_add_u32_e32 v163, s75, v160
	ds_read_b128 v[130:133], v142
	ds_read_b128 v[134:137], v142 offset:1024
	ds_read_b128 v[138:141], v142 offset:2048
	ds_read_b128 v[142:145], v142 offset:3072
	ds_read_b128 v[156:159], v163
	ds_read_b128 v[164:167], v163 offset:1024
	ds_read_b128 v[168:171], v163 offset:2048
	ds_read_b128 v[172:175], v163 offset:3072
	ds_read_b128 v[176:179], v162
	ds_read_b128 v[180:183], v162 offset:1024
	ds_read_b128 v[184:187], v162 offset:2048
	ds_read_b128 v[210:213], v162 offset:3072
	ds_read_b128 v[214:217], v162 offset:4096
	ds_read_b128 v[218:221], v162 offset:5120
	ds_read_b128 v[222:225], v162 offset:6144
	ds_read_b128 v[226:229], v162 offset:7168
	s_add_i32 m0, s53, 0xc000
	s_nop 0
	global_load_lds_dwordx4 v152, s[40:41]
	s_add_i32 m0, s53, 0xe000
	s_nop 0
	global_load_lds_dwordx4 v154, s[40:41]
	s_waitcnt vmcnt(8)
	s_waitcnt lgkmcnt(0)
	s_barrier
	s_setprio 1
	s_waitcnt lgkmcnt(0)
	v_mfma_f32_16x16x32_bf16 v[126:129], v[130:133], v[176:179], v[126:129]
	v_mfma_f32_16x16x32_bf16 v[126:129], v[134:137], v[180:183], v[126:129]
	v_mfma_f32_16x16x32_bf16 v[114:117], v[134:137], v[210:213], v[114:117]
	v_mfma_f32_16x16x32_bf16 v[114:117], v[130:133], v[184:187], v[114:117]
	v_mfma_f32_16x16x32_bf16 v[98:101], v[130:133], v[214:217], v[98:101]
	v_mfma_f32_16x16x32_bf16 v[98:101], v[134:137], v[218:221], v[98:101]
	v_mfma_f32_16x16x32_bf16 v[82:85], v[134:137], v[226:229], v[82:85]
	v_mfma_f32_16x16x32_bf16 v[82:85], v[130:133], v[222:225], v[82:85]
	v_mfma_f32_16x16x32_bf16 v[74:77], v[138:141], v[222:225], v[74:77]
	v_mfma_f32_16x16x32_bf16 v[74:77], v[142:145], v[226:229], v[74:77]
	v_mfma_f32_16x16x32_bf16 v[90:93], v[142:145], v[218:221], v[90:93]
	v_mfma_f32_16x16x32_bf16 v[90:93], v[138:141], v[214:217], v[90:93]
	v_mfma_f32_16x16x32_bf16 v[106:109], v[138:141], v[184:187], v[106:109]
	v_mfma_f32_16x16x32_bf16 v[106:109], v[142:145], v[210:213], v[106:109]
	v_mfma_f32_16x16x32_bf16 v[122:125], v[142:145], v[180:183], v[122:125]
	v_mfma_f32_16x16x32_bf16 v[122:125], v[138:141], v[176:179], v[122:125]
	v_mfma_f32_16x16x32_bf16 v[110:113], v[168:171], v[176:179], v[110:113]
	v_mfma_f32_16x16x32_bf16 v[110:113], v[172:175], v[180:183], v[110:113]
	v_mfma_f32_16x16x32_bf16 v[94:97], v[172:175], v[210:213], v[94:97]
	v_mfma_f32_16x16x32_bf16 v[94:97], v[168:171], v[184:187], v[94:97]
	v_mfma_f32_16x16x32_bf16 v[78:81], v[168:171], v[214:217], v[78:81]
	v_mfma_f32_16x16x32_bf16 v[78:81], v[172:175], v[218:221], v[78:81]
	v_mfma_f32_16x16x32_bf16 v[66:69], v[172:175], v[226:229], v[66:69]
	v_mfma_f32_16x16x32_bf16 v[66:69], v[168:171], v[222:225], v[66:69]
	v_mfma_f32_16x16x32_bf16 v[70:73], v[156:159], v[222:225], v[70:73]
	v_mfma_f32_16x16x32_bf16 v[70:73], v[164:167], v[226:229], v[70:73]
	v_mfma_f32_16x16x32_bf16 v[86:89], v[164:167], v[218:221], v[86:89]
	v_mfma_f32_16x16x32_bf16 v[86:89], v[156:159], v[214:217], v[86:89]
	v_mfma_f32_16x16x32_bf16 v[102:105], v[156:159], v[184:187], v[102:105]
	v_mfma_f32_16x16x32_bf16 v[102:105], v[164:167], v[210:213], v[102:105]
	v_mfma_f32_16x16x32_bf16 v[118:121], v[164:167], v[180:183], v[118:121]
	v_mfma_f32_16x16x32_bf16 v[118:121], v[156:159], v[176:179], v[118:121]
	s_setprio 0
	s_barrier
	s_add_i32 s12, s56, s59
	ds_read_b128 v[176:179], v162 offset:16384
	ds_read_b128 v[180:183], v162 offset:17408
	ds_read_b128 v[184:187], v162 offset:18432
	ds_read_b128 v[210:213], v162 offset:19456
	ds_read_b128 v[214:217], v162 offset:20480
	ds_read_b128 v[218:221], v162 offset:21504
	ds_read_b128 v[222:225], v162 offset:22528
	ds_read_b128 v[226:229], v162 offset:23552
	s_mov_b32 m0, s12
	s_nop 0
	global_load_lds_dwordx4 v190, s[54:55]
	s_add_i32 m0, s12, 0x2000
	s_add_u32 s12, s54, 0x40000
	s_addc_u32 s13, s55, 0
	s_add_i32 s56, s75, s59
	global_load_lds_dwordx4 v150, s[54:55]
	s_mov_b32 m0, s56
	s_nop 0
	global_load_lds_dwordx4 v190, s[12:13]
	s_add_i32 m0, s56, 0x2000
	s_nop 0
	global_load_lds_dwordx4 v150, s[12:13]
	s_mov_b32 m0, s53
	s_nop 0
	global_load_lds_dwordx4 v146, s[62:63]
	s_mov_b32 m0, s60
	s_nop 0
	global_load_lds_dwordx4 v148, s[62:63]
	s_waitcnt vmcnt(8)
	s_waitcnt lgkmcnt(0)
	s_barrier
	s_setprio 1
	s_waitcnt lgkmcnt(0)
	v_mfma_f32_16x16x32_bf16 v[62:65], v[130:133], v[176:179], v[62:65]
	v_mfma_f32_16x16x32_bf16 v[62:65], v[134:137], v[180:183], v[62:65]
	v_mfma_f32_16x16x32_bf16 v[50:53], v[134:137], v[210:213], v[50:53]
	v_mfma_f32_16x16x32_bf16 v[50:53], v[130:133], v[184:187], v[50:53]
	v_mfma_f32_16x16x32_bf16 v[34:37], v[130:133], v[214:217], v[34:37]
	v_mfma_f32_16x16x32_bf16 v[34:37], v[134:137], v[218:221], v[34:37]
	v_mfma_f32_16x16x32_bf16 v[18:21], v[134:137], v[226:229], v[18:21]
	v_mfma_f32_16x16x32_bf16 v[18:21], v[130:133], v[222:225], v[18:21]
	v_mfma_f32_16x16x32_bf16 v[10:13], v[138:141], v[222:225], v[10:13]
	v_mfma_f32_16x16x32_bf16 v[10:13], v[142:145], v[226:229], v[10:13]
	v_mfma_f32_16x16x32_bf16 v[26:29], v[142:145], v[218:221], v[26:29]
	v_mfma_f32_16x16x32_bf16 v[26:29], v[138:141], v[214:217], v[26:29]
	v_mfma_f32_16x16x32_bf16 v[42:45], v[138:141], v[184:187], v[42:45]
	v_mfma_f32_16x16x32_bf16 v[42:45], v[142:145], v[210:213], v[42:45]
	v_mfma_f32_16x16x32_bf16 v[58:61], v[142:145], v[180:183], v[58:61]
	v_mfma_f32_16x16x32_bf16 v[58:61], v[138:141], v[176:179], v[58:61]
	v_mfma_f32_16x16x32_bf16 v[46:49], v[168:171], v[176:179], v[46:49]
	v_mfma_f32_16x16x32_bf16 v[46:49], v[172:175], v[180:183], v[46:49]
	v_mfma_f32_16x16x32_bf16 v[30:33], v[172:175], v[210:213], v[30:33]
	v_mfma_f32_16x16x32_bf16 v[30:33], v[168:171], v[184:187], v[30:33]
	v_mfma_f32_16x16x32_bf16 v[14:17], v[168:171], v[214:217], v[14:17]
	v_mfma_f32_16x16x32_bf16 v[14:17], v[172:175], v[218:221], v[14:17]
	v_mfma_f32_16x16x32_bf16 v[2:5], v[172:175], v[226:229], v[2:5]
	v_mfma_f32_16x16x32_bf16 v[2:5], v[168:171], v[222:225], v[2:5]
	v_mfma_f32_16x16x32_bf16 v[6:9], v[156:159], v[222:225], v[6:9]
	v_mfma_f32_16x16x32_bf16 v[6:9], v[164:167], v[226:229], v[6:9]
	v_mfma_f32_16x16x32_bf16 v[22:25], v[164:167], v[218:221], v[22:25]
	v_mfma_f32_16x16x32_bf16 v[22:25], v[156:159], v[214:217], v[22:25]
	v_mfma_f32_16x16x32_bf16 v[38:41], v[156:159], v[184:187], v[38:41]
	v_mfma_f32_16x16x32_bf16 v[38:41], v[164:167], v[210:213], v[38:41]
	v_mfma_f32_16x16x32_bf16 v[54:57], v[164:167], v[180:183], v[54:57]
	v_mfma_f32_16x16x32_bf16 v[54:57], v[156:159], v[176:179], v[54:57]
	s_setprio 0
	s_barrier
	s_add_i32 s56, 0, 0x18000
	s_add_i32 s75, 0, 0x1c000
	s_add_u32 s12, s62, 0x40000
	s_addc_u32 s13, s63, 0
	v_add_u32_e32 v142, s56, v160
	v_add_u32_e32 v163, s75, v160
	ds_read_b128 v[130:133], v142
	ds_read_b128 v[134:137], v142 offset:1024
	ds_read_b128 v[138:141], v142 offset:2048
	ds_read_b128 v[142:145], v142 offset:3072
	ds_read_b128 v[156:159], v163
	ds_read_b128 v[164:167], v163 offset:1024
	ds_read_b128 v[168:171], v163 offset:2048
	ds_read_b128 v[172:175], v163 offset:3072
	ds_read_b128 v[176:179], v162 offset:32768
	ds_read_b128 v[180:183], v162 offset:33792
	ds_read_b128 v[184:187], v162 offset:34816
	ds_read_b128 v[210:213], v162 offset:35840
	ds_read_b128 v[214:217], v162 offset:36864
	ds_read_b128 v[218:221], v162 offset:37888
	ds_read_b128 v[222:225], v162 offset:38912
	ds_read_b128 v[226:229], v162 offset:39936
	s_mov_b32 m0, s64
	s_nop 0
	global_load_lds_dwordx4 v146, s[12:13]
	s_mov_b32 m0, s65
	s_nop 0
	global_load_lds_dwordx4 v148, s[12:13]
	s_waitcnt vmcnt(8)
	s_waitcnt lgkmcnt(0)
	s_barrier
	s_setprio 1
	s_waitcnt lgkmcnt(0)
	v_mfma_f32_16x16x32_bf16 v[126:129], v[130:133], v[176:179], v[126:129]
	v_mfma_f32_16x16x32_bf16 v[126:129], v[134:137], v[180:183], v[126:129]
	v_mfma_f32_16x16x32_bf16 v[114:117], v[134:137], v[210:213], v[114:117]
	v_mfma_f32_16x16x32_bf16 v[114:117], v[130:133], v[184:187], v[114:117]
	v_mfma_f32_16x16x32_bf16 v[98:101], v[130:133], v[214:217], v[98:101]
	v_mfma_f32_16x16x32_bf16 v[98:101], v[134:137], v[218:221], v[98:101]
	v_mfma_f32_16x16x32_bf16 v[82:85], v[134:137], v[226:229], v[82:85]
	v_mfma_f32_16x16x32_bf16 v[82:85], v[130:133], v[222:225], v[82:85]
	v_mfma_f32_16x16x32_bf16 v[74:77], v[138:141], v[222:225], v[74:77]
	v_mfma_f32_16x16x32_bf16 v[74:77], v[142:145], v[226:229], v[74:77]
	v_mfma_f32_16x16x32_bf16 v[90:93], v[142:145], v[218:221], v[90:93]
	v_mfma_f32_16x16x32_bf16 v[90:93], v[138:141], v[214:217], v[90:93]
	v_mfma_f32_16x16x32_bf16 v[106:109], v[138:141], v[184:187], v[106:109]
	v_mfma_f32_16x16x32_bf16 v[106:109], v[142:145], v[210:213], v[106:109]
	v_mfma_f32_16x16x32_bf16 v[122:125], v[142:145], v[180:183], v[122:125]
	v_mfma_f32_16x16x32_bf16 v[122:125], v[138:141], v[176:179], v[122:125]
	v_mfma_f32_16x16x32_bf16 v[110:113], v[168:171], v[176:179], v[110:113]
	v_mfma_f32_16x16x32_bf16 v[110:113], v[172:175], v[180:183], v[110:113]
	v_mfma_f32_16x16x32_bf16 v[94:97], v[172:175], v[210:213], v[94:97]
	v_mfma_f32_16x16x32_bf16 v[94:97], v[168:171], v[184:187], v[94:97]
	v_mfma_f32_16x16x32_bf16 v[78:81], v[168:171], v[214:217], v[78:81]
	v_mfma_f32_16x16x32_bf16 v[78:81], v[172:175], v[218:221], v[78:81]
	v_mfma_f32_16x16x32_bf16 v[66:69], v[172:175], v[226:229], v[66:69]
	v_mfma_f32_16x16x32_bf16 v[66:69], v[168:171], v[222:225], v[66:69]
	v_mfma_f32_16x16x32_bf16 v[70:73], v[156:159], v[222:225], v[70:73]
	v_mfma_f32_16x16x32_bf16 v[70:73], v[164:167], v[226:229], v[70:73]
	v_mfma_f32_16x16x32_bf16 v[86:89], v[164:167], v[218:221], v[86:89]
	v_mfma_f32_16x16x32_bf16 v[86:89], v[156:159], v[214:217], v[86:89]
	v_mfma_f32_16x16x32_bf16 v[102:105], v[156:159], v[184:187], v[102:105]
	v_mfma_f32_16x16x32_bf16 v[102:105], v[164:167], v[210:213], v[102:105]
	v_mfma_f32_16x16x32_bf16 v[118:121], v[164:167], v[180:183], v[118:121]
	v_mfma_f32_16x16x32_bf16 v[118:121], v[156:159], v[176:179], v[118:121]
	s_setprio 0
	s_barrier
	s_add_i32 s12, s56, s59
	ds_read_b128 v[176:179], v162 offset:49152
	ds_read_b128 v[180:183], v162 offset:50176
	ds_read_b128 v[184:187], v162 offset:51200
	ds_read_b128 v[210:213], v162 offset:52224
	ds_read_b128 v[214:217], v162 offset:53248
	ds_read_b128 v[218:221], v162 offset:54272
	ds_read_b128 v[222:225], v162 offset:55296
	ds_read_b128 v[226:229], v162 offset:56320
	s_mov_b32 m0, s12
	s_nop 0
	global_load_lds_dwordx4 v231, s[54:55]
	s_add_i32 m0, s12, 0x2000
	s_add_u32 s12, s54, 0x40080
	s_addc_u32 s13, s55, 0
	global_load_lds_dwordx4 v230, s[54:55]
	s_add_i32 s54, s75, s59
	s_mov_b32 m0, s54
	s_nop 0
	global_load_lds_dwordx4 v190, s[12:13]
	s_add_i32 m0, s54, 0x2000
	s_nop 0
	global_load_lds_dwordx4 v150, s[12:13]
	s_mov_b32 m0, s66
	s_nop 0
	global_load_lds_dwordx4 v188, s[62:63]
	s_mov_b32 m0, s68
	s_nop 0
	global_load_lds_dwordx4 v189, s[62:63]
	s_waitcnt vmcnt(8)
	s_waitcnt lgkmcnt(0)
	s_barrier
	s_setprio 1
	s_waitcnt lgkmcnt(0)
	v_mfma_f32_16x16x32_bf16 v[62:65], v[130:133], v[176:179], v[62:65]
	v_mfma_f32_16x16x32_bf16 v[62:65], v[134:137], v[180:183], v[62:65]
	v_mfma_f32_16x16x32_bf16 v[50:53], v[134:137], v[210:213], v[50:53]
	v_mfma_f32_16x16x32_bf16 v[50:53], v[130:133], v[184:187], v[50:53]
	v_mfma_f32_16x16x32_bf16 v[34:37], v[130:133], v[214:217], v[34:37]
	v_mfma_f32_16x16x32_bf16 v[34:37], v[134:137], v[218:221], v[34:37]
	v_mfma_f32_16x16x32_bf16 v[18:21], v[134:137], v[226:229], v[18:21]
	v_mfma_f32_16x16x32_bf16 v[18:21], v[130:133], v[222:225], v[18:21]
	v_mfma_f32_16x16x32_bf16 v[10:13], v[138:141], v[222:225], v[10:13]
	v_mfma_f32_16x16x32_bf16 v[10:13], v[142:145], v[226:229], v[10:13]
	v_mfma_f32_16x16x32_bf16 v[26:29], v[142:145], v[218:221], v[26:29]
	v_mfma_f32_16x16x32_bf16 v[26:29], v[138:141], v[214:217], v[26:29]
	v_mfma_f32_16x16x32_bf16 v[42:45], v[138:141], v[184:187], v[42:45]
	v_mfma_f32_16x16x32_bf16 v[42:45], v[142:145], v[210:213], v[42:45]
	v_mfma_f32_16x16x32_bf16 v[58:61], v[142:145], v[180:183], v[58:61]
	v_mfma_f32_16x16x32_bf16 v[58:61], v[138:141], v[176:179], v[58:61]
	v_mfma_f32_16x16x32_bf16 v[46:49], v[168:171], v[176:179], v[46:49]
	v_mfma_f32_16x16x32_bf16 v[46:49], v[172:175], v[180:183], v[46:49]
	v_mfma_f32_16x16x32_bf16 v[30:33], v[172:175], v[210:213], v[30:33]
	v_mfma_f32_16x16x32_bf16 v[30:33], v[168:171], v[184:187], v[30:33]
	v_mfma_f32_16x16x32_bf16 v[14:17], v[168:171], v[214:217], v[14:17]
	v_mfma_f32_16x16x32_bf16 v[14:17], v[172:175], v[218:221], v[14:17]
	v_mfma_f32_16x16x32_bf16 v[2:5], v[172:175], v[226:229], v[2:5]
	v_mfma_f32_16x16x32_bf16 v[2:5], v[168:171], v[222:225], v[2:5]
	v_mfma_f32_16x16x32_bf16 v[6:9], v[156:159], v[222:225], v[6:9]
	v_mfma_f32_16x16x32_bf16 v[6:9], v[164:167], v[226:229], v[6:9]
	v_mfma_f32_16x16x32_bf16 v[22:25], v[164:167], v[218:221], v[22:25]
	v_mfma_f32_16x16x32_bf16 v[22:25], v[156:159], v[214:217], v[22:25]
	v_mfma_f32_16x16x32_bf16 v[38:41], v[156:159], v[184:187], v[38:41]
	v_mfma_f32_16x16x32_bf16 v[38:41], v[164:167], v[210:213], v[38:41]
	v_mfma_f32_16x16x32_bf16 v[54:57], v[164:167], v[180:183], v[54:57]
	v_mfma_f32_16x16x32_bf16 v[54:57], v[156:159], v[176:179], v[54:57]
	s_setprio 0
	s_barrier
	s_add_i32 s74, s74, 2
	s_add_u32 s40, s40, 0x100
	s_addc_u32 s41, s41, 0
	s_add_u32 s73, s73, 0x100
	s_addc_u32 s61, s61, 0
	s_cmp_gt_u32 s74, 13
	s_cbranch_scc0 .LBB0_692
	s_and_b64 vcc, exec, s[30:31]
	s_cbranch_vccz .LBB0_695
	s_barrier

.LBB0_777:
	s_add_u32 s12, s50, 0xfff00080
	s_addc_u32 s13, s51, -1
	s_add_i32 s56, 0, 0x10000
	s_cmp_eq_u32 s72, 60
	s_cselect_b32 s55, s43, s13
	s_cselect_b32 s54, s49, s12
	s_cselect_b32 s53, s41, s61
	s_cselect_b32 s52, s70, s71
	s_add_i32 s73, 0, 0x14000
	v_add_u32_e32 v142, s56, v193
	v_add_u32_e32 v158, s73, v193
	ds_read_b128 v[130:133], v142
	ds_read_b128 v[134:137], v142 offset:1024
	ds_read_b128 v[138:141], v142 offset:2048
	ds_read_b128 v[142:145], v142 offset:3072
	ds_read_b128 v[146:149], v158
	ds_read_b128 v[150:153], v158 offset:1024
	ds_read_b128 v[154:157], v158 offset:2048
	ds_read_b128 v[158:161], v158 offset:3072
	ds_read_b128 v[162:165], v197
	ds_read_b128 v[166:169], v197 offset:1024
	ds_read_b128 v[170:173], v197 offset:2048
	ds_read_b128 v[174:177], v197 offset:3072
	ds_read_b128 v[178:181], v197 offset:4096
	ds_read_b128 v[182:185], v197 offset:5120
	ds_read_b128 v[186:189], v197 offset:6144
	ds_read_b128 v[220:223], v197 offset:7168
	s_add_i32 m0, s33, 0xc000
	s_nop 0
	global_load_lds_dwordx4 v216, s[50:51]
	s_add_i32 m0, s33, 0xe000
	s_nop 0
	global_load_lds_dwordx4 v218, s[50:51]
	s_waitcnt vmcnt(8)
	s_waitcnt lgkmcnt(0)
	s_barrier
	s_setprio 1
	s_waitcnt lgkmcnt(0)
	v_mfma_f32_16x16x32_bf16 v[126:129], v[130:133], v[162:165], v[126:129]
	v_mfma_f32_16x16x32_bf16 v[126:129], v[134:137], v[166:169], v[126:129]
	v_mfma_f32_16x16x32_bf16 v[110:113], v[134:137], v[174:177], v[110:113]
	v_mfma_f32_16x16x32_bf16 v[110:113], v[130:133], v[170:173], v[110:113]
	v_mfma_f32_16x16x32_bf16 v[98:101], v[130:133], v[178:181], v[98:101]
	v_mfma_f32_16x16x32_bf16 v[98:101], v[134:137], v[182:185], v[98:101]
	v_mfma_f32_16x16x32_bf16 v[82:85], v[134:137], v[220:223], v[82:85]
	v_mfma_f32_16x16x32_bf16 v[82:85], v[130:133], v[186:189], v[82:85]
	v_mfma_f32_16x16x32_bf16 v[74:77], v[138:141], v[186:189], v[74:77]
	v_mfma_f32_16x16x32_bf16 v[74:77], v[142:145], v[220:223], v[74:77]
	v_mfma_f32_16x16x32_bf16 v[90:93], v[142:145], v[182:185], v[90:93]
	v_mfma_f32_16x16x32_bf16 v[90:93], v[138:141], v[178:181], v[90:93]
	v_mfma_f32_16x16x32_bf16 v[106:109], v[138:141], v[170:173], v[106:109]
	v_mfma_f32_16x16x32_bf16 v[106:109], v[142:145], v[174:177], v[106:109]
	v_mfma_f32_16x16x32_bf16 v[122:125], v[142:145], v[166:169], v[122:125]
	v_mfma_f32_16x16x32_bf16 v[122:125], v[138:141], v[162:165], v[122:125]
	v_mfma_f32_16x16x32_bf16 v[114:117], v[154:157], v[162:165], v[114:117]
	v_mfma_f32_16x16x32_bf16 v[114:117], v[158:161], v[166:169], v[114:117]
	v_mfma_f32_16x16x32_bf16 v[94:97], v[158:161], v[174:177], v[94:97]
	v_mfma_f32_16x16x32_bf16 v[94:97], v[154:157], v[170:173], v[94:97]
	v_mfma_f32_16x16x32_bf16 v[78:81], v[154:157], v[178:181], v[78:81]
	v_mfma_f32_16x16x32_bf16 v[78:81], v[158:161], v[182:185], v[78:81]
	v_mfma_f32_16x16x32_bf16 v[66:69], v[158:161], v[220:223], v[66:69]
	v_mfma_f32_16x16x32_bf16 v[66:69], v[154:157], v[186:189], v[66:69]
	v_mfma_f32_16x16x32_bf16 v[70:73], v[146:149], v[186:189], v[70:73]
	v_mfma_f32_16x16x32_bf16 v[70:73], v[150:153], v[220:223], v[70:73]
	v_mfma_f32_16x16x32_bf16 v[86:89], v[150:153], v[182:185], v[86:89]
	v_mfma_f32_16x16x32_bf16 v[86:89], v[146:149], v[178:181], v[86:89]
	v_mfma_f32_16x16x32_bf16 v[102:105], v[146:149], v[170:173], v[102:105]
	v_mfma_f32_16x16x32_bf16 v[102:105], v[150:153], v[174:177], v[102:105]
	v_mfma_f32_16x16x32_bf16 v[118:121], v[150:153], v[166:169], v[118:121]
	v_mfma_f32_16x16x32_bf16 v[118:121], v[146:149], v[162:165], v[118:121]
	s_setprio 0
	s_barrier
	s_add_i32 s12, s56, s29
	ds_read_b128 v[162:165], v197 offset:16384
	ds_read_b128 v[166:169], v197 offset:17408
	ds_read_b128 v[170:173], v197 offset:18432
	ds_read_b128 v[174:177], v197 offset:19456
	ds_read_b128 v[178:181], v197 offset:20480
	ds_read_b128 v[182:185], v197 offset:21504
	ds_read_b128 v[186:189], v197 offset:22528
	ds_read_b128 v[220:223], v197 offset:23552
	s_mov_b32 m0, s12
	s_nop 0
	global_load_lds_dwordx4 v190, s[52:53]
	s_add_i32 m0, s12, 0x2000
	s_add_u32 s12, s52, 0x100000
	s_addc_u32 s13, s53, 0
	s_add_i32 s56, s73, s29
	global_load_lds_dwordx4 v214, s[52:53]
	s_mov_b32 m0, s56
	s_nop 0
	global_load_lds_dwordx4 v190, s[12:13]
	s_add_i32 m0, s56, 0x2000
	s_nop 0
	global_load_lds_dwordx4 v214, s[12:13]
	s_mov_b32 m0, s33
	s_nop 0
	global_load_lds_dwordx4 v210, s[54:55]
	s_mov_b32 m0, s62
	s_nop 0
	global_load_lds_dwordx4 v212, s[54:55]
	s_waitcnt vmcnt(8)
	s_waitcnt lgkmcnt(0)
	s_barrier
	s_setprio 1
	s_waitcnt lgkmcnt(0)
	v_mfma_f32_16x16x32_bf16 v[62:65], v[130:133], v[162:165], v[62:65]
	v_mfma_f32_16x16x32_bf16 v[62:65], v[134:137], v[166:169], v[62:65]
	v_mfma_f32_16x16x32_bf16 v[50:53], v[134:137], v[174:177], v[50:53]
	v_mfma_f32_16x16x32_bf16 v[50:53], v[130:133], v[170:173], v[50:53]
	v_mfma_f32_16x16x32_bf16 v[34:37], v[130:133], v[178:181], v[34:37]
	v_mfma_f32_16x16x32_bf16 v[34:37], v[134:137], v[182:185], v[34:37]
	v_mfma_f32_16x16x32_bf16 v[18:21], v[134:137], v[220:223], v[18:21]
	v_mfma_f32_16x16x32_bf16 v[18:21], v[130:133], v[186:189], v[18:21]
	v_mfma_f32_16x16x32_bf16 v[10:13], v[138:141], v[186:189], v[10:13]
	v_mfma_f32_16x16x32_bf16 v[10:13], v[142:145], v[220:223], v[10:13]
	v_mfma_f32_16x16x32_bf16 v[26:29], v[142:145], v[182:185], v[26:29]
	v_mfma_f32_16x16x32_bf16 v[26:29], v[138:141], v[178:181], v[26:29]
	v_mfma_f32_16x16x32_bf16 v[42:45], v[138:141], v[170:173], v[42:45]
	v_mfma_f32_16x16x32_bf16 v[42:45], v[142:145], v[174:177], v[42:45]
	v_mfma_f32_16x16x32_bf16 v[58:61], v[142:145], v[166:169], v[58:61]
	v_mfma_f32_16x16x32_bf16 v[58:61], v[138:141], v[162:165], v[58:61]
	v_mfma_f32_16x16x32_bf16 v[46:49], v[154:157], v[162:165], v[46:49]
	v_mfma_f32_16x16x32_bf16 v[46:49], v[158:161], v[166:169], v[46:49]
	v_mfma_f32_16x16x32_bf16 v[30:33], v[158:161], v[174:177], v[30:33]
	v_mfma_f32_16x16x32_bf16 v[30:33], v[154:157], v[170:173], v[30:33]
	v_mfma_f32_16x16x32_bf16 v[14:17], v[154:157], v[178:181], v[14:17]
	v_mfma_f32_16x16x32_bf16 v[14:17], v[158:161], v[182:185], v[14:17]
	v_mfma_f32_16x16x32_bf16 v[2:5], v[158:161], v[220:223], v[2:5]
	v_mfma_f32_16x16x32_bf16 v[2:5], v[154:157], v[186:189], v[2:5]
	v_mfma_f32_16x16x32_bf16 v[6:9], v[146:149], v[186:189], v[6:9]
	v_mfma_f32_16x16x32_bf16 v[6:9], v[150:153], v[220:223], v[6:9]
	v_mfma_f32_16x16x32_bf16 v[22:25], v[150:153], v[182:185], v[22:25]
	v_mfma_f32_16x16x32_bf16 v[22:25], v[146:149], v[178:181], v[22:25]
	v_mfma_f32_16x16x32_bf16 v[38:41], v[146:149], v[170:173], v[38:41]
	v_mfma_f32_16x16x32_bf16 v[38:41], v[150:153], v[174:177], v[38:41]
	v_mfma_f32_16x16x32_bf16 v[54:57], v[150:153], v[166:169], v[54:57]
	v_mfma_f32_16x16x32_bf16 v[54:57], v[146:149], v[162:165], v[54:57]
	s_setprio 0
	s_barrier
	s_add_i32 s56, 0, 0x18000
	s_add_i32 s73, 0, 0x1c000
	s_add_u32 s12, s54, 0x100000
	s_addc_u32 s13, s55, 0
	v_add_u32_e32 v142, s56, v193
	v_add_u32_e32 v158, s73, v193
	ds_read_b128 v[130:133], v142
	ds_read_b128 v[134:137], v142 offset:1024
	ds_read_b128 v[138:141], v142 offset:2048
	ds_read_b128 v[142:145], v142 offset:3072
	ds_read_b128 v[146:149], v158
	ds_read_b128 v[150:153], v158 offset:1024
	ds_read_b128 v[154:157], v158 offset:2048
	ds_read_b128 v[158:161], v158 offset:3072
	ds_read_b128 v[162:165], v197 offset:32768
	ds_read_b128 v[166:169], v197 offset:33792
	ds_read_b128 v[170:173], v197 offset:34816
	ds_read_b128 v[174:177], v197 offset:35840
	ds_read_b128 v[178:181], v197 offset:36864
	ds_read_b128 v[182:185], v197 offset:37888
	ds_read_b128 v[186:189], v197 offset:38912
	ds_read_b128 v[220:223], v197 offset:39936
	s_mov_b32 m0, s63
	s_nop 0
	global_load_lds_dwordx4 v210, s[12:13]
	s_mov_b32 m0, s64
	s_nop 0
	global_load_lds_dwordx4 v212, s[12:13]
	s_waitcnt vmcnt(8)
	s_waitcnt lgkmcnt(0)
	s_barrier
	s_setprio 1
	s_waitcnt lgkmcnt(0)
	v_mfma_f32_16x16x32_bf16 v[126:129], v[130:133], v[162:165], v[126:129]
	v_mfma_f32_16x16x32_bf16 v[126:129], v[134:137], v[166:169], v[126:129]
	v_mfma_f32_16x16x32_bf16 v[110:113], v[134:137], v[174:177], v[110:113]
	v_mfma_f32_16x16x32_bf16 v[110:113], v[130:133], v[170:173], v[110:113]
	v_mfma_f32_16x16x32_bf16 v[98:101], v[130:133], v[178:181], v[98:101]
	v_mfma_f32_16x16x32_bf16 v[98:101], v[134:137], v[182:185], v[98:101]
	v_mfma_f32_16x16x32_bf16 v[82:85], v[134:137], v[220:223], v[82:85]
	v_mfma_f32_16x16x32_bf16 v[82:85], v[130:133], v[186:189], v[82:85]
	v_mfma_f32_16x16x32_bf16 v[74:77], v[138:141], v[186:189], v[74:77]
	v_mfma_f32_16x16x32_bf16 v[74:77], v[142:145], v[220:223], v[74:77]
	v_mfma_f32_16x16x32_bf16 v[90:93], v[142:145], v[182:185], v[90:93]
	v_mfma_f32_16x16x32_bf16 v[90:93], v[138:141], v[178:181], v[90:93]
	v_mfma_f32_16x16x32_bf16 v[106:109], v[138:141], v[170:173], v[106:109]
	v_mfma_f32_16x16x32_bf16 v[106:109], v[142:145], v[174:177], v[106:109]
	v_mfma_f32_16x16x32_bf16 v[122:125], v[142:145], v[166:169], v[122:125]
	v_mfma_f32_16x16x32_bf16 v[122:125], v[138:141], v[162:165], v[122:125]
	v_mfma_f32_16x16x32_bf16 v[114:117], v[154:157], v[162:165], v[114:117]
	v_mfma_f32_16x16x32_bf16 v[114:117], v[158:161], v[166:169], v[114:117]
	v_mfma_f32_16x16x32_bf16 v[94:97], v[158:161], v[174:177], v[94:97]
	v_mfma_f32_16x16x32_bf16 v[94:97], v[154:157], v[170:173], v[94:97]
	v_mfma_f32_16x16x32_bf16 v[78:81], v[154:157], v[178:181], v[78:81]
	v_mfma_f32_16x16x32_bf16 v[78:81], v[158:161], v[182:185], v[78:81]
	v_mfma_f32_16x16x32_bf16 v[66:69], v[158:161], v[220:223], v[66:69]
	v_mfma_f32_16x16x32_bf16 v[66:69], v[154:157], v[186:189], v[66:69]
	v_mfma_f32_16x16x32_bf16 v[70:73], v[146:149], v[186:189], v[70:73]
	v_mfma_f32_16x16x32_bf16 v[70:73], v[150:153], v[220:223], v[70:73]
	v_mfma_f32_16x16x32_bf16 v[86:89], v[150:153], v[182:185], v[86:89]
	v_mfma_f32_16x16x32_bf16 v[86:89], v[146:149], v[178:181], v[86:89]
	v_mfma_f32_16x16x32_bf16 v[102:105], v[146:149], v[170:173], v[102:105]
	v_mfma_f32_16x16x32_bf16 v[102:105], v[150:153], v[174:177], v[102:105]
	v_mfma_f32_16x16x32_bf16 v[118:121], v[150:153], v[166:169], v[118:121]
	v_mfma_f32_16x16x32_bf16 v[118:121], v[146:149], v[162:165], v[118:121]
	s_setprio 0
	s_barrier
	s_add_i32 s12, s56, s29
	ds_read_b128 v[162:165], v197 offset:49152
	ds_read_b128 v[166:169], v197 offset:50176
	ds_read_b128 v[170:173], v197 offset:51200
	ds_read_b128 v[174:177], v197 offset:52224
	ds_read_b128 v[178:181], v197 offset:53248
	ds_read_b128 v[182:185], v197 offset:54272
	ds_read_b128 v[186:189], v197 offset:55296
	ds_read_b128 v[220:223], v197 offset:56320
	s_mov_b32 m0, s12
	s_nop 0
	global_load_lds_dwordx4 v224, s[52:53]
	s_add_i32 m0, s12, 0x2000
	s_add_u32 s12, s52, 0x100080
	s_addc_u32 s13, s53, 0
	global_load_lds_dwordx4 v227, s[52:53]
	s_add_i32 s52, s73, s29
	s_mov_b32 m0, s52
	s_nop 0
	global_load_lds_dwordx4 v190, s[12:13]
	s_add_i32 m0, s52, 0x2000
	s_nop 0
	global_load_lds_dwordx4 v214, s[12:13]
	s_mov_b32 m0, s65
	s_nop 0
	global_load_lds_dwordx4 v225, s[54:55]
	s_mov_b32 m0, s66
	s_nop 0
	global_load_lds_dwordx4 v226, s[54:55]
	s_waitcnt vmcnt(8)
	s_waitcnt lgkmcnt(0)
	s_barrier
	s_setprio 1
	s_waitcnt lgkmcnt(0)
	v_mfma_f32_16x16x32_bf16 v[62:65], v[130:133], v[162:165], v[62:65]
	v_mfma_f32_16x16x32_bf16 v[62:65], v[134:137], v[166:169], v[62:65]
	v_mfma_f32_16x16x32_bf16 v[50:53], v[134:137], v[174:177], v[50:53]
	v_mfma_f32_16x16x32_bf16 v[50:53], v[130:133], v[170:173], v[50:53]
	v_mfma_f32_16x16x32_bf16 v[34:37], v[130:133], v[178:181], v[34:37]
	v_mfma_f32_16x16x32_bf16 v[34:37], v[134:137], v[182:185], v[34:37]
	v_mfma_f32_16x16x32_bf16 v[18:21], v[134:137], v[220:223], v[18:21]
	v_mfma_f32_16x16x32_bf16 v[18:21], v[130:133], v[186:189], v[18:21]
	v_mfma_f32_16x16x32_bf16 v[10:13], v[138:141], v[186:189], v[10:13]
	v_mfma_f32_16x16x32_bf16 v[10:13], v[142:145], v[220:223], v[10:13]
	v_mfma_f32_16x16x32_bf16 v[26:29], v[142:145], v[182:185], v[26:29]
	v_mfma_f32_16x16x32_bf16 v[26:29], v[138:141], v[178:181], v[26:29]
	v_mfma_f32_16x16x32_bf16 v[42:45], v[138:141], v[170:173], v[42:45]
	v_mfma_f32_16x16x32_bf16 v[42:45], v[142:145], v[174:177], v[42:45]
	v_mfma_f32_16x16x32_bf16 v[58:61], v[142:145], v[166:169], v[58:61]
	v_mfma_f32_16x16x32_bf16 v[58:61], v[138:141], v[162:165], v[58:61]
	v_mfma_f32_16x16x32_bf16 v[46:49], v[154:157], v[162:165], v[46:49]
	v_mfma_f32_16x16x32_bf16 v[46:49], v[158:161], v[166:169], v[46:49]
	v_mfma_f32_16x16x32_bf16 v[30:33], v[158:161], v[174:177], v[30:33]
	v_mfma_f32_16x16x32_bf16 v[30:33], v[154:157], v[170:173], v[30:33]
	v_mfma_f32_16x16x32_bf16 v[14:17], v[154:157], v[178:181], v[14:17]
	v_mfma_f32_16x16x32_bf16 v[14:17], v[158:161], v[182:185], v[14:17]
	v_mfma_f32_16x16x32_bf16 v[2:5], v[158:161], v[220:223], v[2:5]
	v_mfma_f32_16x16x32_bf16 v[2:5], v[154:157], v[186:189], v[2:5]
	v_mfma_f32_16x16x32_bf16 v[6:9], v[146:149], v[186:189], v[6:9]
	v_mfma_f32_16x16x32_bf16 v[6:9], v[150:153], v[220:223], v[6:9]
	v_mfma_f32_16x16x32_bf16 v[22:25], v[150:153], v[182:185], v[22:25]
	v_mfma_f32_16x16x32_bf16 v[22:25], v[146:149], v[178:181], v[22:25]
	v_mfma_f32_16x16x32_bf16 v[38:41], v[146:149], v[170:173], v[38:41]
	v_mfma_f32_16x16x32_bf16 v[38:41], v[150:153], v[174:177], v[38:41]
	v_mfma_f32_16x16x32_bf16 v[54:57], v[150:153], v[166:169], v[54:57]
	v_mfma_f32_16x16x32_bf16 v[54:57], v[146:149], v[162:165], v[54:57]
	s_setprio 0
	s_barrier
	s_add_i32 s72, s72, 2
	s_add_u32 s50, s50, 0x100
	s_addc_u32 s51, s51, 0
	s_add_u32 s71, s71, 0x100
	s_addc_u32 s61, s61, 0
	s_cmp_gt_u32 s72, 61
	s_cbranch_scc0 .LBB0_777
	s_and_b64 vcc, exec, s[30:31]
	s_cbranch_vccz .LBB0_780
	s_barrier

.LBB0_902:
	s_add_u32 s12, s22, 0xfff00080
	s_addc_u32 s13, s23, -1
	s_add_i32 s56, 0, 0x10000
	s_cmp_eq_u32 s47, 60
	s_cselect_b32 s53, s5, s13
	s_cselect_b32 s52, s10, s12
	s_cselect_b32 s31, s25, s45
	s_cselect_b32 s30, s29, s33
	s_add_i32 s61, 0, 0x14000
	v_add_u32_e32 v147, s56, v144
	ds_read_b128 v[140:143], v147
	ds_read_b128 v[148:151], v147 offset:1024
	ds_read_b128 v[152:155], v147 offset:2048
	ds_read_b128 v[156:159], v147 offset:3072
	v_add_u32_e32 v147, s61, v144
	ds_read_b128 v[160:163], v147
	ds_read_b128 v[164:167], v147 offset:1024
	ds_read_b128 v[168:171], v147 offset:2048
	ds_read_b128 v[172:175], v147 offset:3072
	ds_read_b128 v[176:179], v146
	ds_read_b128 v[180:183], v146 offset:1024
	ds_read_b128 v[184:187], v146 offset:2048
	ds_read_b128 v[210:213], v146 offset:3072
	ds_read_b128 v[214:217], v146 offset:4096
	ds_read_b128 v[218:221], v146 offset:5120
	ds_read_b128 v[222:225], v146 offset:6144
	ds_read_b128 v[226:229], v146 offset:7168
	s_add_i32 m0, s63, 0xc000
	s_nop 0
	global_load_lds_dwordx4 v136, s[22:23]
	s_add_i32 m0, s63, 0xe000
	s_nop 0
	global_load_lds_dwordx4 v138, s[22:23]
	s_waitcnt vmcnt(8)
	s_waitcnt lgkmcnt(0)
	s_barrier
	s_setprio 1
	s_waitcnt lgkmcnt(0)
	v_mfma_f32_16x16x32_bf16 v[126:129], v[140:143], v[176:179], v[126:129]
	v_mfma_f32_16x16x32_bf16 v[126:129], v[148:151], v[180:183], v[126:129]
	v_mfma_f32_16x16x32_bf16 v[110:113], v[148:151], v[210:213], v[110:113]
	v_mfma_f32_16x16x32_bf16 v[110:113], v[140:143], v[184:187], v[110:113]
	v_mfma_f32_16x16x32_bf16 v[94:97], v[140:143], v[214:217], v[94:97]
	v_mfma_f32_16x16x32_bf16 v[94:97], v[148:151], v[218:221], v[94:97]
	v_mfma_f32_16x16x32_bf16 v[78:81], v[148:151], v[226:229], v[78:81]
	v_mfma_f32_16x16x32_bf16 v[78:81], v[140:143], v[222:225], v[78:81]
	v_mfma_f32_16x16x32_bf16 v[70:73], v[152:155], v[222:225], v[70:73]
	v_mfma_f32_16x16x32_bf16 v[70:73], v[156:159], v[226:229], v[70:73]
	v_mfma_f32_16x16x32_bf16 v[86:89], v[156:159], v[218:221], v[86:89]
	v_mfma_f32_16x16x32_bf16 v[86:89], v[152:155], v[214:217], v[86:89]
	v_mfma_f32_16x16x32_bf16 v[102:105], v[152:155], v[184:187], v[102:105]
	v_mfma_f32_16x16x32_bf16 v[102:105], v[156:159], v[210:213], v[102:105]
	v_mfma_f32_16x16x32_bf16 v[118:121], v[156:159], v[180:183], v[118:121]
	v_mfma_f32_16x16x32_bf16 v[118:121], v[152:155], v[176:179], v[118:121]
	v_mfma_f32_16x16x32_bf16 v[114:117], v[168:171], v[176:179], v[114:117]
	v_mfma_f32_16x16x32_bf16 v[114:117], v[172:175], v[180:183], v[114:117]
	v_mfma_f32_16x16x32_bf16 v[98:101], v[172:175], v[210:213], v[98:101]
	v_mfma_f32_16x16x32_bf16 v[98:101], v[168:171], v[184:187], v[98:101]
	v_mfma_f32_16x16x32_bf16 v[82:85], v[168:171], v[214:217], v[82:85]
	v_mfma_f32_16x16x32_bf16 v[82:85], v[172:175], v[218:221], v[82:85]
	v_mfma_f32_16x16x32_bf16 v[66:69], v[172:175], v[226:229], v[66:69]
	v_mfma_f32_16x16x32_bf16 v[66:69], v[168:171], v[222:225], v[66:69]
	v_mfma_f32_16x16x32_bf16 v[74:77], v[160:163], v[222:225], v[74:77]
	v_mfma_f32_16x16x32_bf16 v[74:77], v[164:167], v[226:229], v[74:77]
	v_mfma_f32_16x16x32_bf16 v[90:93], v[164:167], v[218:221], v[90:93]
	v_mfma_f32_16x16x32_bf16 v[90:93], v[160:163], v[214:217], v[90:93]
	v_mfma_f32_16x16x32_bf16 v[106:109], v[160:163], v[184:187], v[106:109]
	v_mfma_f32_16x16x32_bf16 v[106:109], v[164:167], v[210:213], v[106:109]
	v_mfma_f32_16x16x32_bf16 v[122:125], v[164:167], v[180:183], v[122:125]
	v_mfma_f32_16x16x32_bf16 v[122:125], v[160:163], v[176:179], v[122:125]
	s_setprio 0
	s_barrier
	s_add_i32 s12, s56, s60
	ds_read_b128 v[176:179], v146 offset:16384
	ds_read_b128 v[180:183], v146 offset:17408
	ds_read_b128 v[184:187], v146 offset:18432
	ds_read_b128 v[210:213], v146 offset:19456
	ds_read_b128 v[214:217], v146 offset:20480
	ds_read_b128 v[218:221], v146 offset:21504
	ds_read_b128 v[222:225], v146 offset:22528
	ds_read_b128 v[226:229], v146 offset:23552
	s_mov_b32 m0, s12
	s_nop 0
	global_load_lds_dwordx4 v190, s[30:31]
	s_add_i32 m0, s12, 0x2000
	s_add_u32 s12, s30, 0x100000
	s_addc_u32 s13, s31, 0
	s_add_i32 s56, s61, s60
	global_load_lds_dwordx4 v130, s[30:31]
	s_mov_b32 m0, s56
	s_nop 0
	global_load_lds_dwordx4 v190, s[12:13]
	s_add_i32 m0, s56, 0x2000
	s_nop 0
	global_load_lds_dwordx4 v130, s[12:13]
	s_mov_b32 m0, s63
	s_nop 0
	global_load_lds_dwordx4 v134, s[52:53]
	s_mov_b32 m0, s64
	s_nop 0
	global_load_lds_dwordx4 v132, s[52:53]
	s_waitcnt vmcnt(8)
	s_waitcnt lgkmcnt(0)
	s_barrier
	s_setprio 1
	s_waitcnt lgkmcnt(0)
	v_mfma_f32_16x16x32_bf16 v[62:65], v[140:143], v[176:179], v[62:65]
	v_mfma_f32_16x16x32_bf16 v[62:65], v[148:151], v[180:183], v[62:65]
	v_mfma_f32_16x16x32_bf16 v[46:49], v[148:151], v[210:213], v[46:49]
	v_mfma_f32_16x16x32_bf16 v[46:49], v[140:143], v[184:187], v[46:49]
	v_mfma_f32_16x16x32_bf16 v[30:33], v[140:143], v[214:217], v[30:33]
	v_mfma_f32_16x16x32_bf16 v[30:33], v[148:151], v[218:221], v[30:33]
	v_mfma_f32_16x16x32_bf16 v[14:17], v[148:151], v[226:229], v[14:17]
	v_mfma_f32_16x16x32_bf16 v[14:17], v[140:143], v[222:225], v[14:17]
	v_mfma_f32_16x16x32_bf16 v[6:9], v[152:155], v[222:225], v[6:9]
	v_mfma_f32_16x16x32_bf16 v[6:9], v[156:159], v[226:229], v[6:9]
	v_mfma_f32_16x16x32_bf16 v[22:25], v[156:159], v[218:221], v[22:25]
	v_mfma_f32_16x16x32_bf16 v[22:25], v[152:155], v[214:217], v[22:25]
	v_mfma_f32_16x16x32_bf16 v[38:41], v[152:155], v[184:187], v[38:41]
	v_mfma_f32_16x16x32_bf16 v[38:41], v[156:159], v[210:213], v[38:41]
	v_mfma_f32_16x16x32_bf16 v[54:57], v[156:159], v[180:183], v[54:57]
	v_mfma_f32_16x16x32_bf16 v[54:57], v[152:155], v[176:179], v[54:57]
	v_mfma_f32_16x16x32_bf16 v[50:53], v[168:171], v[176:179], v[50:53]
	v_mfma_f32_16x16x32_bf16 v[50:53], v[172:175], v[180:183], v[50:53]
	v_mfma_f32_16x16x32_bf16 v[34:37], v[172:175], v[210:213], v[34:37]
	v_mfma_f32_16x16x32_bf16 v[34:37], v[168:171], v[184:187], v[34:37]
	v_mfma_f32_16x16x32_bf16 v[18:21], v[168:171], v[214:217], v[18:21]
	v_mfma_f32_16x16x32_bf16 v[18:21], v[172:175], v[218:221], v[18:21]
	v_mfma_f32_16x16x32_bf16 v[2:5], v[172:175], v[226:229], v[2:5]
	v_mfma_f32_16x16x32_bf16 v[2:5], v[168:171], v[222:225], v[2:5]
	v_mfma_f32_16x16x32_bf16 v[10:13], v[160:163], v[222:225], v[10:13]
	v_mfma_f32_16x16x32_bf16 v[10:13], v[164:167], v[226:229], v[10:13]
	v_mfma_f32_16x16x32_bf16 v[26:29], v[164:167], v[218:221], v[26:29]
	v_mfma_f32_16x16x32_bf16 v[26:29], v[160:163], v[214:217], v[26:29]
	v_mfma_f32_16x16x32_bf16 v[42:45], v[160:163], v[184:187], v[42:45]
	v_mfma_f32_16x16x32_bf16 v[42:45], v[164:167], v[210:213], v[42:45]
	v_mfma_f32_16x16x32_bf16 v[58:61], v[164:167], v[180:183], v[58:61]
	v_mfma_f32_16x16x32_bf16 v[58:61], v[160:163], v[176:179], v[58:61]
	s_setprio 0
	s_barrier
	s_add_i32 s56, 0, 0x18000
	s_add_i32 s61, 0, 0x1c000
	s_add_u32 s12, s52, 0x100000
	s_addc_u32 s13, s53, 0
	v_add_u32_e32 v147, s56, v144
	ds_read_b128 v[140:143], v147
	ds_read_b128 v[148:151], v147 offset:1024
	ds_read_b128 v[152:155], v147 offset:2048
	ds_read_b128 v[156:159], v147 offset:3072
	v_add_u32_e32 v147, s61, v144
	ds_read_b128 v[160:163], v147
	ds_read_b128 v[164:167], v147 offset:1024
	ds_read_b128 v[168:171], v147 offset:2048
	ds_read_b128 v[172:175], v147 offset:3072
	ds_read_b128 v[176:179], v146 offset:32768
	ds_read_b128 v[180:183], v146 offset:33792
	ds_read_b128 v[184:187], v146 offset:34816
	ds_read_b128 v[210:213], v146 offset:35840
	ds_read_b128 v[214:217], v146 offset:36864
	ds_read_b128 v[218:221], v146 offset:37888
	ds_read_b128 v[222:225], v146 offset:38912
	ds_read_b128 v[226:229], v146 offset:39936
	s_mov_b32 m0, s65
	s_nop 0
	global_load_lds_dwordx4 v134, s[12:13]
	s_mov_b32 m0, s66
	s_nop 0
	global_load_lds_dwordx4 v132, s[12:13]
	s_waitcnt vmcnt(8)
	s_waitcnt lgkmcnt(0)
	s_barrier
	s_setprio 1
	s_waitcnt lgkmcnt(0)
	v_mfma_f32_16x16x32_bf16 v[126:129], v[140:143], v[176:179], v[126:129]
	v_mfma_f32_16x16x32_bf16 v[126:129], v[148:151], v[180:183], v[126:129]
	v_mfma_f32_16x16x32_bf16 v[110:113], v[148:151], v[210:213], v[110:113]
	v_mfma_f32_16x16x32_bf16 v[110:113], v[140:143], v[184:187], v[110:113]
	v_mfma_f32_16x16x32_bf16 v[94:97], v[140:143], v[214:217], v[94:97]
	v_mfma_f32_16x16x32_bf16 v[94:97], v[148:151], v[218:221], v[94:97]
	v_mfma_f32_16x16x32_bf16 v[78:81], v[148:151], v[226:229], v[78:81]
	v_mfma_f32_16x16x32_bf16 v[78:81], v[140:143], v[222:225], v[78:81]
	v_mfma_f32_16x16x32_bf16 v[70:73], v[152:155], v[222:225], v[70:73]
	v_mfma_f32_16x16x32_bf16 v[70:73], v[156:159], v[226:229], v[70:73]
	v_mfma_f32_16x16x32_bf16 v[86:89], v[156:159], v[218:221], v[86:89]
	v_mfma_f32_16x16x32_bf16 v[86:89], v[152:155], v[214:217], v[86:89]
	v_mfma_f32_16x16x32_bf16 v[102:105], v[152:155], v[184:187], v[102:105]
	v_mfma_f32_16x16x32_bf16 v[102:105], v[156:159], v[210:213], v[102:105]
	v_mfma_f32_16x16x32_bf16 v[118:121], v[156:159], v[180:183], v[118:121]
	v_mfma_f32_16x16x32_bf16 v[118:121], v[152:155], v[176:179], v[118:121]
	v_mfma_f32_16x16x32_bf16 v[114:117], v[168:171], v[176:179], v[114:117]
	v_mfma_f32_16x16x32_bf16 v[114:117], v[172:175], v[180:183], v[114:117]
	v_mfma_f32_16x16x32_bf16 v[98:101], v[172:175], v[210:213], v[98:101]
	v_mfma_f32_16x16x32_bf16 v[98:101], v[168:171], v[184:187], v[98:101]
	v_mfma_f32_16x16x32_bf16 v[82:85], v[168:171], v[214:217], v[82:85]
	v_mfma_f32_16x16x32_bf16 v[82:85], v[172:175], v[218:221], v[82:85]
	v_mfma_f32_16x16x32_bf16 v[66:69], v[172:175], v[226:229], v[66:69]
	v_mfma_f32_16x16x32_bf16 v[66:69], v[168:171], v[222:225], v[66:69]
	v_mfma_f32_16x16x32_bf16 v[74:77], v[160:163], v[222:225], v[74:77]
	v_mfma_f32_16x16x32_bf16 v[74:77], v[164:167], v[226:229], v[74:77]
	v_mfma_f32_16x16x32_bf16 v[90:93], v[164:167], v[218:221], v[90:93]
	v_mfma_f32_16x16x32_bf16 v[90:93], v[160:163], v[214:217], v[90:93]
	v_mfma_f32_16x16x32_bf16 v[106:109], v[160:163], v[184:187], v[106:109]
	v_mfma_f32_16x16x32_bf16 v[106:109], v[164:167], v[210:213], v[106:109]
	v_mfma_f32_16x16x32_bf16 v[122:125], v[164:167], v[180:183], v[122:125]
	v_mfma_f32_16x16x32_bf16 v[122:125], v[160:163], v[176:179], v[122:125]
	s_setprio 0
	s_barrier
	s_add_i32 s12, s56, s60
	ds_read_b128 v[176:179], v146 offset:49152
	ds_read_b128 v[180:183], v146 offset:50176
	ds_read_b128 v[184:187], v146 offset:51200
	ds_read_b128 v[210:213], v146 offset:52224
	ds_read_b128 v[214:217], v146 offset:53248
	ds_read_b128 v[218:221], v146 offset:54272
	ds_read_b128 v[222:225], v146 offset:55296
	ds_read_b128 v[226:229], v146 offset:56320
	s_mov_b32 m0, s12
	s_nop 0
	global_load_lds_dwordx4 v231, s[30:31]
	s_add_i32 m0, s12, 0x2000
	s_add_u32 s12, s30, 0x100080
	s_addc_u32 s13, s31, 0
	global_load_lds_dwordx4 v188, s[30:31]
	s_add_i32 s30, s61, s60
	s_mov_b32 m0, s30
	s_nop 0
	global_load_lds_dwordx4 v190, s[12:13]
	s_add_i32 m0, s30, 0x2000
	s_nop 0
	global_load_lds_dwordx4 v130, s[12:13]
	s_mov_b32 m0, s68
	s_nop 0
	global_load_lds_dwordx4 v230, s[52:53]
	s_mov_b32 m0, s69
	s_nop 0
	global_load_lds_dwordx4 v189, s[52:53]
	s_waitcnt vmcnt(8)
	s_waitcnt lgkmcnt(0)
	s_barrier
	s_setprio 1
	s_waitcnt lgkmcnt(0)
	v_mfma_f32_16x16x32_bf16 v[62:65], v[140:143], v[176:179], v[62:65]
	v_mfma_f32_16x16x32_bf16 v[62:65], v[148:151], v[180:183], v[62:65]
	v_mfma_f32_16x16x32_bf16 v[46:49], v[148:151], v[210:213], v[46:49]
	v_mfma_f32_16x16x32_bf16 v[46:49], v[140:143], v[184:187], v[46:49]
	v_mfma_f32_16x16x32_bf16 v[30:33], v[140:143], v[214:217], v[30:33]
	v_mfma_f32_16x16x32_bf16 v[30:33], v[148:151], v[218:221], v[30:33]
	v_mfma_f32_16x16x32_bf16 v[14:17], v[148:151], v[226:229], v[14:17]
	v_mfma_f32_16x16x32_bf16 v[14:17], v[140:143], v[222:225], v[14:17]
	v_mfma_f32_16x16x32_bf16 v[6:9], v[152:155], v[222:225], v[6:9]
	v_mfma_f32_16x16x32_bf16 v[6:9], v[156:159], v[226:229], v[6:9]
	v_mfma_f32_16x16x32_bf16 v[22:25], v[156:159], v[218:221], v[22:25]
	v_mfma_f32_16x16x32_bf16 v[22:25], v[152:155], v[214:217], v[22:25]
	v_mfma_f32_16x16x32_bf16 v[38:41], v[152:155], v[184:187], v[38:41]
	v_mfma_f32_16x16x32_bf16 v[38:41], v[156:159], v[210:213], v[38:41]
	v_mfma_f32_16x16x32_bf16 v[54:57], v[156:159], v[180:183], v[54:57]
	v_mfma_f32_16x16x32_bf16 v[54:57], v[152:155], v[176:179], v[54:57]
	v_mfma_f32_16x16x32_bf16 v[50:53], v[168:171], v[176:179], v[50:53]
	v_mfma_f32_16x16x32_bf16 v[50:53], v[172:175], v[180:183], v[50:53]
	v_mfma_f32_16x16x32_bf16 v[34:37], v[172:175], v[210:213], v[34:37]
	v_mfma_f32_16x16x32_bf16 v[34:37], v[168:171], v[184:187], v[34:37]
	v_mfma_f32_16x16x32_bf16 v[18:21], v[168:171], v[214:217], v[18:21]
	v_mfma_f32_16x16x32_bf16 v[18:21], v[172:175], v[218:221], v[18:21]
	v_mfma_f32_16x16x32_bf16 v[2:5], v[172:175], v[226:229], v[2:5]
	v_mfma_f32_16x16x32_bf16 v[2:5], v[168:171], v[222:225], v[2:5]
	v_mfma_f32_16x16x32_bf16 v[10:13], v[160:163], v[222:225], v[10:13]
	v_mfma_f32_16x16x32_bf16 v[10:13], v[164:167], v[226:229], v[10:13]
	v_mfma_f32_16x16x32_bf16 v[26:29], v[164:167], v[218:221], v[26:29]
	v_mfma_f32_16x16x32_bf16 v[26:29], v[160:163], v[214:217], v[26:29]
	v_mfma_f32_16x16x32_bf16 v[42:45], v[160:163], v[184:187], v[42:45]
	v_mfma_f32_16x16x32_bf16 v[42:45], v[164:167], v[210:213], v[42:45]
	v_mfma_f32_16x16x32_bf16 v[58:61], v[164:167], v[180:183], v[58:61]
	v_mfma_f32_16x16x32_bf16 v[58:61], v[160:163], v[176:179], v[58:61]
	s_setprio 0
	s_barrier
	s_add_i32 s47, s47, 2
	s_add_u32 s22, s22, 0x100
	s_addc_u32 s23, s23, 0
	s_add_u32 s33, s33, 0x100
	s_addc_u32 s45, s45, 0
	s_cmp_gt_u32 s47, 61
	s_cbranch_scc0 .LBB0_902
	s_and_b64 vcc, exec, s[42:43]
	s_cbranch_vccz .LBB0_905
	s_barrier

.LBB0_983:
	s_add_u32 s46, s44, 0x100
	s_addc_u32 s47, s45, 0
	s_add_i32 s12, 0, 0x10000
	s_cmpk_eq_i32 s70, 0xa8
	s_cselect_b32 s51, s41, s47
	s_cselect_b32 s50, s40, s46
	s_cselect_b32 s49, s43, s69
	s_cselect_b32 s48, s42, s61
	s_add_i32 s56, 0, 0x14000
	v_add_u32_e32 v142, s12, v193
	v_add_u32_e32 v158, s56, v193
	ds_read_b128 v[130:133], v142
	ds_read_b128 v[134:137], v142 offset:1024
	ds_read_b128 v[138:141], v142 offset:2048
	ds_read_b128 v[142:145], v142 offset:3072
	ds_read_b128 v[146:149], v158
	ds_read_b128 v[150:153], v158 offset:1024
	ds_read_b128 v[154:157], v158 offset:2048
	ds_read_b128 v[158:161], v158 offset:3072
	ds_read_b128 v[162:165], v197
	ds_read_b128 v[166:169], v197 offset:1024
	ds_read_b128 v[170:173], v197 offset:2048
	ds_read_b128 v[174:177], v197 offset:3072
	ds_read_b128 v[178:181], v197 offset:4096
	ds_read_b128 v[182:185], v197 offset:5120
	ds_read_b128 v[186:189], v197 offset:6144
	ds_read_b128 v[220:223], v197 offset:7168
	s_add_i32 m0, s33, 0xc000
	s_nop 0
	global_load_lds_dwordx4 v216, s[44:45]
	s_add_i32 m0, s33, 0xe000
	s_nop 0
	global_load_lds_dwordx4 v218, s[44:45]
	s_waitcnt vmcnt(8)
	s_waitcnt lgkmcnt(0)
	s_barrier
	s_setprio 1
	s_waitcnt lgkmcnt(0)
	v_mfma_f32_16x16x32_bf16 v[126:129], v[130:133], v[162:165], v[126:129]
	v_mfma_f32_16x16x32_bf16 v[126:129], v[134:137], v[166:169], v[126:129]
	v_mfma_f32_16x16x32_bf16 v[110:113], v[134:137], v[174:177], v[110:113]
	v_mfma_f32_16x16x32_bf16 v[110:113], v[130:133], v[170:173], v[110:113]
	v_mfma_f32_16x16x32_bf16 v[98:101], v[130:133], v[178:181], v[98:101]
	v_mfma_f32_16x16x32_bf16 v[98:101], v[134:137], v[182:185], v[98:101]
	v_mfma_f32_16x16x32_bf16 v[82:85], v[134:137], v[220:223], v[82:85]
	v_mfma_f32_16x16x32_bf16 v[82:85], v[130:133], v[186:189], v[82:85]
	v_mfma_f32_16x16x32_bf16 v[74:77], v[138:141], v[186:189], v[74:77]
	v_mfma_f32_16x16x32_bf16 v[74:77], v[142:145], v[220:223], v[74:77]
	v_mfma_f32_16x16x32_bf16 v[90:93], v[142:145], v[182:185], v[90:93]
	v_mfma_f32_16x16x32_bf16 v[90:93], v[138:141], v[178:181], v[90:93]
	v_mfma_f32_16x16x32_bf16 v[106:109], v[138:141], v[170:173], v[106:109]
	v_mfma_f32_16x16x32_bf16 v[106:109], v[142:145], v[174:177], v[106:109]
	v_mfma_f32_16x16x32_bf16 v[122:125], v[142:145], v[166:169], v[122:125]
	v_mfma_f32_16x16x32_bf16 v[122:125], v[138:141], v[162:165], v[122:125]
	v_mfma_f32_16x16x32_bf16 v[114:117], v[154:157], v[162:165], v[114:117]
	v_mfma_f32_16x16x32_bf16 v[114:117], v[158:161], v[166:169], v[114:117]
	v_mfma_f32_16x16x32_bf16 v[94:97], v[158:161], v[174:177], v[94:97]
	v_mfma_f32_16x16x32_bf16 v[94:97], v[154:157], v[170:173], v[94:97]
	v_mfma_f32_16x16x32_bf16 v[78:81], v[154:157], v[178:181], v[78:81]
	v_mfma_f32_16x16x32_bf16 v[78:81], v[158:161], v[182:185], v[78:81]
	v_mfma_f32_16x16x32_bf16 v[66:69], v[158:161], v[220:223], v[66:69]
	v_mfma_f32_16x16x32_bf16 v[66:69], v[154:157], v[186:189], v[66:69]
	v_mfma_f32_16x16x32_bf16 v[70:73], v[146:149], v[186:189], v[70:73]
	v_mfma_f32_16x16x32_bf16 v[70:73], v[150:153], v[220:223], v[70:73]
	v_mfma_f32_16x16x32_bf16 v[86:89], v[150:153], v[182:185], v[86:89]
	v_mfma_f32_16x16x32_bf16 v[86:89], v[146:149], v[178:181], v[86:89]
	v_mfma_f32_16x16x32_bf16 v[102:105], v[146:149], v[170:173], v[102:105]
	v_mfma_f32_16x16x32_bf16 v[102:105], v[150:153], v[174:177], v[102:105]
	v_mfma_f32_16x16x32_bf16 v[118:121], v[150:153], v[166:169], v[118:121]
	v_mfma_f32_16x16x32_bf16 v[118:121], v[146:149], v[162:165], v[118:121]
	s_setprio 0
	s_barrier
	s_add_i32 s12, s12, s29
	ds_read_b128 v[162:165], v197 offset:16384
	ds_read_b128 v[166:169], v197 offset:17408
	ds_read_b128 v[170:173], v197 offset:18432
	ds_read_b128 v[174:177], v197 offset:19456
	ds_read_b128 v[178:181], v197 offset:20480
	ds_read_b128 v[182:185], v197 offset:21504
	ds_read_b128 v[186:189], v197 offset:22528
	ds_read_b128 v[220:223], v197 offset:23552
	s_mov_b32 m0, s12
	s_nop 0
	global_load_lds_dwordx4 v190, s[48:49]
	s_add_i32 m0, s12, 0x2000
	s_add_u32 s12, s48, 0x2b0000
	s_addc_u32 s13, s49, 0
	s_add_i32 s44, s56, s29
	global_load_lds_dwordx4 v214, s[48:49]
	s_mov_b32 m0, s44
	s_nop 0
	global_load_lds_dwordx4 v190, s[12:13]
	s_add_i32 m0, s44, 0x2000
	s_nop 0
	global_load_lds_dwordx4 v214, s[12:13]
	s_mov_b32 m0, s33
	s_nop 0
	global_load_lds_dwordx4 v210, s[50:51]
	s_mov_b32 m0, s57
	s_nop 0
	global_load_lds_dwordx4 v212, s[50:51]
	s_waitcnt vmcnt(8)
	s_waitcnt lgkmcnt(0)
	s_barrier
	s_setprio 1
	s_waitcnt lgkmcnt(0)
	v_mfma_f32_16x16x32_bf16 v[62:65], v[130:133], v[162:165], v[62:65]
	v_mfma_f32_16x16x32_bf16 v[62:65], v[134:137], v[166:169], v[62:65]
	v_mfma_f32_16x16x32_bf16 v[50:53], v[134:137], v[174:177], v[50:53]
	v_mfma_f32_16x16x32_bf16 v[50:53], v[130:133], v[170:173], v[50:53]
	v_mfma_f32_16x16x32_bf16 v[34:37], v[130:133], v[178:181], v[34:37]
	v_mfma_f32_16x16x32_bf16 v[34:37], v[134:137], v[182:185], v[34:37]
	v_mfma_f32_16x16x32_bf16 v[18:21], v[134:137], v[220:223], v[18:21]
	v_mfma_f32_16x16x32_bf16 v[18:21], v[130:133], v[186:189], v[18:21]
	v_mfma_f32_16x16x32_bf16 v[10:13], v[138:141], v[186:189], v[10:13]
	v_mfma_f32_16x16x32_bf16 v[10:13], v[142:145], v[220:223], v[10:13]
	v_mfma_f32_16x16x32_bf16 v[26:29], v[142:145], v[182:185], v[26:29]
	v_mfma_f32_16x16x32_bf16 v[26:29], v[138:141], v[178:181], v[26:29]
	v_mfma_f32_16x16x32_bf16 v[42:45], v[138:141], v[170:173], v[42:45]
	v_mfma_f32_16x16x32_bf16 v[42:45], v[142:145], v[174:177], v[42:45]
	v_mfma_f32_16x16x32_bf16 v[58:61], v[142:145], v[166:169], v[58:61]
	v_mfma_f32_16x16x32_bf16 v[58:61], v[138:141], v[162:165], v[58:61]
	v_mfma_f32_16x16x32_bf16 v[46:49], v[154:157], v[162:165], v[46:49]
	v_mfma_f32_16x16x32_bf16 v[46:49], v[158:161], v[166:169], v[46:49]
	v_mfma_f32_16x16x32_bf16 v[30:33], v[158:161], v[174:177], v[30:33]
	v_mfma_f32_16x16x32_bf16 v[30:33], v[154:157], v[170:173], v[30:33]
	v_mfma_f32_16x16x32_bf16 v[14:17], v[154:157], v[178:181], v[14:17]
	v_mfma_f32_16x16x32_bf16 v[14:17], v[158:161], v[182:185], v[14:17]
	v_mfma_f32_16x16x32_bf16 v[2:5], v[158:161], v[220:223], v[2:5]
	v_mfma_f32_16x16x32_bf16 v[2:5], v[154:157], v[186:189], v[2:5]
	v_mfma_f32_16x16x32_bf16 v[6:9], v[146:149], v[186:189], v[6:9]
	v_mfma_f32_16x16x32_bf16 v[6:9], v[150:153], v[220:223], v[6:9]
	v_mfma_f32_16x16x32_bf16 v[22:25], v[150:153], v[182:185], v[22:25]
	v_mfma_f32_16x16x32_bf16 v[22:25], v[146:149], v[178:181], v[22:25]
	v_mfma_f32_16x16x32_bf16 v[38:41], v[146:149], v[170:173], v[38:41]
	v_mfma_f32_16x16x32_bf16 v[38:41], v[150:153], v[174:177], v[38:41]
	v_mfma_f32_16x16x32_bf16 v[54:57], v[150:153], v[166:169], v[54:57]
	v_mfma_f32_16x16x32_bf16 v[54:57], v[146:149], v[162:165], v[54:57]
	s_setprio 0
	s_barrier
	s_add_i32 s44, 0, 0x18000
	s_add_i32 s45, 0, 0x1c000
	s_add_u32 s12, s50, 0x2b0000
	s_addc_u32 s13, s51, 0
	v_add_u32_e32 v142, s44, v193
	v_add_u32_e32 v158, s45, v193
	ds_read_b128 v[130:133], v142
	ds_read_b128 v[134:137], v142 offset:1024
	ds_read_b128 v[138:141], v142 offset:2048
	ds_read_b128 v[142:145], v142 offset:3072
	ds_read_b128 v[146:149], v158
	ds_read_b128 v[150:153], v158 offset:1024
	ds_read_b128 v[154:157], v158 offset:2048
	ds_read_b128 v[158:161], v158 offset:3072
	ds_read_b128 v[162:165], v197 offset:32768
	ds_read_b128 v[166:169], v197 offset:33792
	ds_read_b128 v[170:173], v197 offset:34816
	ds_read_b128 v[174:177], v197 offset:35840
	ds_read_b128 v[178:181], v197 offset:36864
	ds_read_b128 v[182:185], v197 offset:37888
	ds_read_b128 v[186:189], v197 offset:38912
	ds_read_b128 v[220:223], v197 offset:39936
	s_mov_b32 m0, s58
	s_nop 0
	global_load_lds_dwordx4 v210, s[12:13]
	s_mov_b32 m0, s59
	s_nop 0
	global_load_lds_dwordx4 v212, s[12:13]
	s_waitcnt vmcnt(8)
	s_waitcnt lgkmcnt(0)
	s_barrier
	s_setprio 1
	s_waitcnt lgkmcnt(0)
	v_mfma_f32_16x16x32_bf16 v[126:129], v[130:133], v[162:165], v[126:129]
	v_mfma_f32_16x16x32_bf16 v[126:129], v[134:137], v[166:169], v[126:129]
	v_mfma_f32_16x16x32_bf16 v[110:113], v[134:137], v[174:177], v[110:113]
	v_mfma_f32_16x16x32_bf16 v[110:113], v[130:133], v[170:173], v[110:113]
	v_mfma_f32_16x16x32_bf16 v[98:101], v[130:133], v[178:181], v[98:101]
	v_mfma_f32_16x16x32_bf16 v[98:101], v[134:137], v[182:185], v[98:101]
	v_mfma_f32_16x16x32_bf16 v[82:85], v[134:137], v[220:223], v[82:85]
	v_mfma_f32_16x16x32_bf16 v[82:85], v[130:133], v[186:189], v[82:85]
	v_mfma_f32_16x16x32_bf16 v[74:77], v[138:141], v[186:189], v[74:77]
	v_mfma_f32_16x16x32_bf16 v[74:77], v[142:145], v[220:223], v[74:77]
	v_mfma_f32_16x16x32_bf16 v[90:93], v[142:145], v[182:185], v[90:93]
	v_mfma_f32_16x16x32_bf16 v[90:93], v[138:141], v[178:181], v[90:93]
	v_mfma_f32_16x16x32_bf16 v[106:109], v[138:141], v[170:173], v[106:109]
	v_mfma_f32_16x16x32_bf16 v[106:109], v[142:145], v[174:177], v[106:109]
	v_mfma_f32_16x16x32_bf16 v[122:125], v[142:145], v[166:169], v[122:125]
	v_mfma_f32_16x16x32_bf16 v[122:125], v[138:141], v[162:165], v[122:125]
	v_mfma_f32_16x16x32_bf16 v[114:117], v[154:157], v[162:165], v[114:117]
	v_mfma_f32_16x16x32_bf16 v[114:117], v[158:161], v[166:169], v[114:117]
	v_mfma_f32_16x16x32_bf16 v[94:97], v[158:161], v[174:177], v[94:97]
	v_mfma_f32_16x16x32_bf16 v[94:97], v[154:157], v[170:173], v[94:97]
	v_mfma_f32_16x16x32_bf16 v[78:81], v[154:157], v[178:181], v[78:81]
	v_mfma_f32_16x16x32_bf16 v[78:81], v[158:161], v[182:185], v[78:81]
	v_mfma_f32_16x16x32_bf16 v[66:69], v[158:161], v[220:223], v[66:69]
	v_mfma_f32_16x16x32_bf16 v[66:69], v[154:157], v[186:189], v[66:69]
	v_mfma_f32_16x16x32_bf16 v[70:73], v[146:149], v[186:189], v[70:73]
	v_mfma_f32_16x16x32_bf16 v[70:73], v[150:153], v[220:223], v[70:73]
	v_mfma_f32_16x16x32_bf16 v[86:89], v[150:153], v[182:185], v[86:89]
	v_mfma_f32_16x16x32_bf16 v[86:89], v[146:149], v[178:181], v[86:89]
	v_mfma_f32_16x16x32_bf16 v[102:105], v[146:149], v[170:173], v[102:105]
	v_mfma_f32_16x16x32_bf16 v[102:105], v[150:153], v[174:177], v[102:105]
	v_mfma_f32_16x16x32_bf16 v[118:121], v[150:153], v[166:169], v[118:121]
	v_mfma_f32_16x16x32_bf16 v[118:121], v[146:149], v[162:165], v[118:121]
	s_setprio 0
	s_barrier
	s_add_i32 s12, s44, s29
	ds_read_b128 v[162:165], v197 offset:49152
	ds_read_b128 v[166:169], v197 offset:50176
	ds_read_b128 v[170:173], v197 offset:51200
	ds_read_b128 v[174:177], v197 offset:52224
	ds_read_b128 v[178:181], v197 offset:53248
	ds_read_b128 v[182:185], v197 offset:54272
	ds_read_b128 v[186:189], v197 offset:55296
	ds_read_b128 v[220:223], v197 offset:56320
	s_mov_b32 m0, s12
	s_nop 0
	global_load_lds_dwordx4 v224, s[48:49]
	s_add_i32 m0, s12, 0x2000
	s_add_u32 s12, s48, 0x2b0080
	s_addc_u32 s13, s49, 0
	s_add_i32 s44, s45, s29
	global_load_lds_dwordx4 v227, s[48:49]
	s_mov_b32 m0, s44
	s_nop 0
	global_load_lds_dwordx4 v190, s[12:13]
	s_add_i32 m0, s44, 0x2000
	s_nop 0
	global_load_lds_dwordx4 v214, s[12:13]
	s_mov_b32 m0, s60
	s_nop 0
	global_load_lds_dwordx4 v225, s[50:51]
	s_mov_b32 m0, s62
	s_nop 0
	global_load_lds_dwordx4 v226, s[50:51]
	s_waitcnt vmcnt(8)
	s_waitcnt lgkmcnt(0)
	s_barrier
	s_setprio 1
	s_waitcnt lgkmcnt(0)
	v_mfma_f32_16x16x32_bf16 v[62:65], v[130:133], v[162:165], v[62:65]
	v_mfma_f32_16x16x32_bf16 v[62:65], v[134:137], v[166:169], v[62:65]
	v_mfma_f32_16x16x32_bf16 v[50:53], v[134:137], v[174:177], v[50:53]
	v_mfma_f32_16x16x32_bf16 v[50:53], v[130:133], v[170:173], v[50:53]
	v_mfma_f32_16x16x32_bf16 v[34:37], v[130:133], v[178:181], v[34:37]
	v_mfma_f32_16x16x32_bf16 v[34:37], v[134:137], v[182:185], v[34:37]
	v_mfma_f32_16x16x32_bf16 v[18:21], v[134:137], v[220:223], v[18:21]
	v_mfma_f32_16x16x32_bf16 v[18:21], v[130:133], v[186:189], v[18:21]
	v_mfma_f32_16x16x32_bf16 v[10:13], v[138:141], v[186:189], v[10:13]
	v_mfma_f32_16x16x32_bf16 v[10:13], v[142:145], v[220:223], v[10:13]
	v_mfma_f32_16x16x32_bf16 v[26:29], v[142:145], v[182:185], v[26:29]
	v_mfma_f32_16x16x32_bf16 v[26:29], v[138:141], v[178:181], v[26:29]
	v_mfma_f32_16x16x32_bf16 v[42:45], v[138:141], v[170:173], v[42:45]
	v_mfma_f32_16x16x32_bf16 v[42:45], v[142:145], v[174:177], v[42:45]
	v_mfma_f32_16x16x32_bf16 v[58:61], v[142:145], v[166:169], v[58:61]
	v_mfma_f32_16x16x32_bf16 v[58:61], v[138:141], v[162:165], v[58:61]
	v_mfma_f32_16x16x32_bf16 v[46:49], v[154:157], v[162:165], v[46:49]
	v_mfma_f32_16x16x32_bf16 v[46:49], v[158:161], v[166:169], v[46:49]
	v_mfma_f32_16x16x32_bf16 v[30:33], v[158:161], v[174:177], v[30:33]
	v_mfma_f32_16x16x32_bf16 v[30:33], v[154:157], v[170:173], v[30:33]
	v_mfma_f32_16x16x32_bf16 v[14:17], v[154:157], v[178:181], v[14:17]
	v_mfma_f32_16x16x32_bf16 v[14:17], v[158:161], v[182:185], v[14:17]
	v_mfma_f32_16x16x32_bf16 v[2:5], v[158:161], v[220:223], v[2:5]
	v_mfma_f32_16x16x32_bf16 v[2:5], v[154:157], v[186:189], v[2:5]
	v_mfma_f32_16x16x32_bf16 v[6:9], v[146:149], v[186:189], v[6:9]
	v_mfma_f32_16x16x32_bf16 v[6:9], v[150:153], v[220:223], v[6:9]
	v_mfma_f32_16x16x32_bf16 v[22:25], v[150:153], v[182:185], v[22:25]
	v_mfma_f32_16x16x32_bf16 v[22:25], v[146:149], v[178:181], v[22:25]
	v_mfma_f32_16x16x32_bf16 v[38:41], v[146:149], v[170:173], v[38:41]
	v_mfma_f32_16x16x32_bf16 v[38:41], v[150:153], v[174:177], v[38:41]
	v_mfma_f32_16x16x32_bf16 v[54:57], v[150:153], v[166:169], v[54:57]
	v_mfma_f32_16x16x32_bf16 v[54:57], v[146:149], v[162:165], v[54:57]
	s_setprio 0
	s_barrier
	s_add_i32 s70, s70, 2
	s_add_u32 s61, s61, 0x100
	s_addc_u32 s69, s69, 0
	s_cmpk_gt_u32 s70, 0xa9
	s_mov_b64 s[44:45], s[46:47]
	s_cbranch_scc0 .LBB0_983
	s_and_b64 vcc, exec, s[30:31]
	s_cbranch_vccz .LBB0_986
	s_barrier
